# adaLN-table phase: k-loop de-serialised - 4 batches of 32 strided loads, two batches in flight with counted vmcnt, LDS rows double-buffered (was 8 loads per trip with vmcnt(0) after the first)
# speedup vs baseline: 1.0123x; 1.0029x over previous
; #define LAS __attribute__((address_space(3)))
; __device__ __forceinline__ void phase_prep(const Args& a, LAS unsigned char* lds) {
;     ...
;             const int l = it / 96, n0 = (it % 96) * 64;
;             const float* w = a.in[2] + (size_t)l * 1024 * 6144 + n0 + lane;
;             float acc[16];
; #pragma unroll
;             for (int b = 0; b < 16; ++b) acc[b] = 0.f;
;             const int kbeg = wave * 128;
; #pragma unroll 8
;             for (int k = kbeg; k < kbeg + 128; ++k) { const float wv = w[(size_t)k * 6144];
;                 const LAS f32x4* s4 = (const LAS f32x4*)(sc + k * 16);
; #pragma unroll
;                 for (int q = 0; q < 4; ++q) { const f32x4 s = s4[q]; acc[4 * q] += s[0] * wv; acc[4 * q + 1] += s[1] * wv; acc[4 * q + 2] += s[2] * wv; acc[4 * q + 3] += s[3] * wv; } }
.LBB0_14:
	s_or_b64 exec, exec, s[10:11]
	s_mul_hi_i32 s10, s27, 0x2aaaaaab
	s_lshr_b32 s11, s10, 31
	s_ashr_i32 s10, s10, 4
	s_add_i32 s12, s10, s11
	s_mul_i32 s10, s12, 0x60
	s_sub_i32 s10, s27, s10
	s_lshl_b32 s10, s10, 6
	s_ashr_i32 s11, s10, 31
	s_ashr_i32 s13, s12, 31
	s_mul_i32 s35, s12, 0x1800000
	s_lshl_b64 s[14:15], s[10:11], 2
	s_mul_hi_i32 s34, s12, 0x1800000
	s_add_u32 s14, s35, s14
	s_addc_u32 s15, s34, s15
	v_mov_b32_e32 v36, 0
	v_lshl_add_u64 v[34:35], v[32:33], 0, s[14:15]
	s_mov_b64 s[14:15], 0
	v_mov_b32_e32 v57, v27
	v_mov_b32_e32 v37, v36
	v_mov_b32_e32 v38, v36
	v_mov_b32_e32 v39, v36
	v_mov_b32_e32 v40, v36
	v_mov_b32_e32 v41, v36
	v_mov_b32_e32 v42, v36
	v_mov_b32_e32 v43, v36
	v_mov_b32_e32 v44, v36
	v_mov_b32_e32 v45, v36
	v_mov_b32_e32 v46, v36
	v_mov_b32_e32 v47, v36
	v_mov_b32_e32 v48, v36
	v_mov_b32_e32 v49, v36
	v_mov_b32_e32 v50, v36
	v_mov_b32_e32 v51, v36
	s_waitcnt lgkmcnt(0)
	s_barrier
	v_readfirstlane_b32 s34, v34
	v_readfirstlane_b32 s35, v35
	v_and_b32_e32 v154, 63, v180
	v_lshlrev_b32_e32 v154, 2, v154
	s_nop 4
	global_load_dword v58, v154, s[34:35]
	s_add_u32 s34, s34, 0x6000
	s_addc_u32 s35, s35, 0
	global_load_dword v59, v154, s[34:35]
	s_add_u32 s34, s34, 0x6000
	s_addc_u32 s35, s35, 0
	global_load_dword v60, v154, s[34:35]
	s_add_u32 s34, s34, 0x6000
	s_addc_u32 s35, s35, 0
	global_load_dword v61, v154, s[34:35]
	s_add_u32 s34, s34, 0x6000
	s_addc_u32 s35, s35, 0
	global_load_dword v62, v154, s[34:35]
	s_add_u32 s34, s34, 0x6000
	s_addc_u32 s35, s35, 0
	global_load_dword v63, v154, s[34:35]
	s_add_u32 s34, s34, 0x6000
	s_addc_u32 s35, s35, 0
	global_load_dword v64, v154, s[34:35]
	s_add_u32 s34, s34, 0x6000
	s_addc_u32 s35, s35, 0
	global_load_dword v65, v154, s[34:35]
	s_add_u32 s34, s34, 0x6000
	s_addc_u32 s35, s35, 0
	global_load_dword v66, v154, s[34:35]
	s_add_u32 s34, s34, 0x6000
	s_addc_u32 s35, s35, 0
	global_load_dword v67, v154, s[34:35]
	s_add_u32 s34, s34, 0x6000
	s_addc_u32 s35, s35, 0
	global_load_dword v68, v154, s[34:35]
	s_add_u32 s34, s34, 0x6000
	s_addc_u32 s35, s35, 0
	global_load_dword v69, v154, s[34:35]
	s_add_u32 s34, s34, 0x6000
	s_addc_u32 s35, s35, 0
	global_load_dword v70, v154, s[34:35]
	s_add_u32 s34, s34, 0x6000
	s_addc_u32 s35, s35, 0
	global_load_dword v71, v154, s[34:35]
	s_add_u32 s34, s34, 0x6000
	s_addc_u32 s35, s35, 0
	global_load_dword v72, v154, s[34:35]
	s_add_u32 s34, s34, 0x6000
	s_addc_u32 s35, s35, 0
	global_load_dword v73, v154, s[34:35]
	s_add_u32 s34, s34, 0x6000
	s_addc_u32 s35, s35, 0
	global_load_dword v74, v154, s[34:35]
	s_add_u32 s34, s34, 0x6000
	s_addc_u32 s35, s35, 0
	global_load_dword v75, v154, s[34:35]
	s_add_u32 s34, s34, 0x6000
	s_addc_u32 s35, s35, 0
	global_load_dword v76, v154, s[34:35]
	s_add_u32 s34, s34, 0x6000
	s_addc_u32 s35, s35, 0
	global_load_dword v77, v154, s[34:35]
	s_add_u32 s34, s34, 0x6000
	s_addc_u32 s35, s35, 0
	global_load_dword v78, v154, s[34:35]
	s_add_u32 s34, s34, 0x6000
	s_addc_u32 s35, s35, 0
	global_load_dword v79, v154, s[34:35]
	s_add_u32 s34, s34, 0x6000
	s_addc_u32 s35, s35, 0
	global_load_dword v80, v154, s[34:35]
	s_add_u32 s34, s34, 0x6000
	s_addc_u32 s35, s35, 0
	global_load_dword v81, v154, s[34:35]
	s_add_u32 s34, s34, 0x6000
	s_addc_u32 s35, s35, 0
	global_load_dword v82, v154, s[34:35]
	s_add_u32 s34, s34, 0x6000
	s_addc_u32 s35, s35, 0
	global_load_dword v83, v154, s[34:35]
	s_add_u32 s34, s34, 0x6000
	s_addc_u32 s35, s35, 0
	global_load_dword v84, v154, s[34:35]
	s_add_u32 s34, s34, 0x6000
	s_addc_u32 s35, s35, 0
	global_load_dword v85, v154, s[34:35]
	s_add_u32 s34, s34, 0x6000
	s_addc_u32 s35, s35, 0
	global_load_dword v86, v154, s[34:35]
	s_add_u32 s34, s34, 0x6000
	s_addc_u32 s35, s35, 0
	global_load_dword v87, v154, s[34:35]
	s_add_u32 s34, s34, 0x6000
	s_addc_u32 s35, s35, 0
	global_load_dword v88, v154, s[34:35]
	s_add_u32 s34, s34, 0x6000
	s_addc_u32 s35, s35, 0
	global_load_dword v89, v154, s[34:35]
	s_add_u32 s34, s34, 0x6000
	s_addc_u32 s35, s35, 0
	global_load_dword v122, v154, s[34:35]
	s_add_u32 s34, s34, 0x6000
	s_addc_u32 s35, s35, 0
	global_load_dword v123, v154, s[34:35]
	s_add_u32 s34, s34, 0x6000
	s_addc_u32 s35, s35, 0
	global_load_dword v124, v154, s[34:35]
	s_add_u32 s34, s34, 0x6000
	s_addc_u32 s35, s35, 0
	global_load_dword v125, v154, s[34:35]
	s_add_u32 s34, s34, 0x6000
	s_addc_u32 s35, s35, 0
	global_load_dword v126, v154, s[34:35]
	s_add_u32 s34, s34, 0x6000
	s_addc_u32 s35, s35, 0
	global_load_dword v127, v154, s[34:35]
	s_add_u32 s34, s34, 0x6000
	s_addc_u32 s35, s35, 0
	global_load_dword v128, v154, s[34:35]
	s_add_u32 s34, s34, 0x6000
	s_addc_u32 s35, s35, 0
	global_load_dword v129, v154, s[34:35]
	s_add_u32 s34, s34, 0x6000
	s_addc_u32 s35, s35, 0
	global_load_dword v130, v154, s[34:35]
	s_add_u32 s34, s34, 0x6000
	s_addc_u32 s35, s35, 0
	global_load_dword v131, v154, s[34:35]
	s_add_u32 s34, s34, 0x6000
	s_addc_u32 s35, s35, 0
	global_load_dword v132, v154, s[34:35]
	s_add_u32 s34, s34, 0x6000
	s_addc_u32 s35, s35, 0
	global_load_dword v133, v154, s[34:35]
	s_add_u32 s34, s34, 0x6000
	s_addc_u32 s35, s35, 0
	global_load_dword v134, v154, s[34:35]
	s_add_u32 s34, s34, 0x6000
	s_addc_u32 s35, s35, 0
	global_load_dword v135, v154, s[34:35]
	s_add_u32 s34, s34, 0x6000
	s_addc_u32 s35, s35, 0
	global_load_dword v136, v154, s[34:35]
	s_add_u32 s34, s34, 0x6000
	s_addc_u32 s35, s35, 0
	global_load_dword v137, v154, s[34:35]
	s_add_u32 s34, s34, 0x6000
	s_addc_u32 s35, s35, 0
	global_load_dword v138, v154, s[34:35]
	s_add_u32 s34, s34, 0x6000
	s_addc_u32 s35, s35, 0
	global_load_dword v139, v154, s[34:35]
	s_add_u32 s34, s34, 0x6000
	s_addc_u32 s35, s35, 0
; #define LAS __attribute__((address_space(3)))
; __device__ __forceinline__ void phase_prep(const Args& a, LAS unsigned char* lds) {
;     ...
;             const int kbeg = wave * 128;
; #pragma unroll 8
;             for (int k = kbeg; k < kbeg + 128; ++k) { const float wv = w[(size_t)k * 6144];
;                 const LAS f32x4* s4 = (const LAS f32x4*)(sc + k * 16);
; #pragma unroll
;                 for (int q = 0; q < 4; ++q) { const f32x4 s = s4[q]; acc[4 * q] += s[0] * wv; acc[4 * q + 1] += s[1] * wv; acc[4 * q + 2] += s[2] * wv; acc[4 * q + 3] += s[3] * wv; } }
	global_load_dword v140, v154, s[34:35]
	s_add_u32 s34, s34, 0x6000
	s_addc_u32 s35, s35, 0
	global_load_dword v141, v154, s[34:35]
	s_add_u32 s34, s34, 0x6000
	s_addc_u32 s35, s35, 0
	global_load_dword v142, v154, s[34:35]
	s_add_u32 s34, s34, 0x6000
	s_addc_u32 s35, s35, 0
	global_load_dword v143, v154, s[34:35]
	s_add_u32 s34, s34, 0x6000
	s_addc_u32 s35, s35, 0
	global_load_dword v144, v154, s[34:35]
	s_add_u32 s34, s34, 0x6000
	s_addc_u32 s35, s35, 0
	global_load_dword v145, v154, s[34:35]
	s_add_u32 s34, s34, 0x6000
	s_addc_u32 s35, s35, 0
	global_load_dword v146, v154, s[34:35]
	s_add_u32 s34, s34, 0x6000
	s_addc_u32 s35, s35, 0
	global_load_dword v147, v154, s[34:35]
	s_add_u32 s34, s34, 0x6000
	s_addc_u32 s35, s35, 0
	global_load_dword v148, v154, s[34:35]
	s_add_u32 s34, s34, 0x6000
	s_addc_u32 s35, s35, 0
	global_load_dword v149, v154, s[34:35]
	s_add_u32 s34, s34, 0x6000
	s_addc_u32 s35, s35, 0
	global_load_dword v150, v154, s[34:35]
	s_add_u32 s34, s34, 0x6000
	s_addc_u32 s35, s35, 0
	global_load_dword v151, v154, s[34:35]
	s_add_u32 s34, s34, 0x6000
	s_addc_u32 s35, s35, 0
	global_load_dword v152, v154, s[34:35]
	s_add_u32 s34, s34, 0x6000
	s_addc_u32 s35, s35, 0
	global_load_dword v153, v154, s[34:35]
	s_add_u32 s34, s34, 0x6000
	s_addc_u32 s35, s35, 0
	ds_read_b128 v[90:93], v57
	ds_read_b128 v[94:97], v57 offset:16
	ds_read_b128 v[98:101], v57 offset:32
	ds_read_b128 v[102:105], v57 offset:48
	ds_read_b128 v[106:109], v57 offset:64
	ds_read_b128 v[110:113], v57 offset:80
	ds_read_b128 v[114:117], v57 offset:96
	ds_read_b128 v[118:121], v57 offset:112
	s_waitcnt vmcnt(63) lgkmcnt(4)
	v_pk_fma_f32 v[38:39], v[58:59], v[90:91], v[38:39] op_sel_hi:[0,1,1]
	v_pk_fma_f32 v[40:41], v[58:59], v[92:93], v[40:41] op_sel_hi:[0,1,1]
	v_pk_fma_f32 v[42:43], v[58:59], v[94:95], v[42:43] op_sel_hi:[0,1,1]
	v_pk_fma_f32 v[44:45], v[58:59], v[96:97], v[44:45] op_sel_hi:[0,1,1]
	v_pk_fma_f32 v[46:47], v[58:59], v[98:99], v[46:47] op_sel_hi:[0,1,1]
	v_pk_fma_f32 v[48:49], v[58:59], v[100:101], v[48:49] op_sel_hi:[0,1,1]
	v_pk_fma_f32 v[50:51], v[58:59], v[102:103], v[50:51] op_sel_hi:[0,1,1]
	v_pk_fma_f32 v[36:37], v[58:59], v[104:105], v[36:37] op_sel_hi:[0,1,1]
	ds_read_b128 v[90:93], v57 offset:128
	ds_read_b128 v[94:97], v57 offset:144
	ds_read_b128 v[98:101], v57 offset:160
	ds_read_b128 v[102:105], v57 offset:176
	s_waitcnt vmcnt(62) lgkmcnt(4)
	v_pk_fma_f32 v[38:39], v[58:59], v[106:107], v[38:39] op_sel:[1,0,0]
	v_pk_fma_f32 v[40:41], v[58:59], v[108:109], v[40:41] op_sel:[1,0,0]
	v_pk_fma_f32 v[42:43], v[58:59], v[110:111], v[42:43] op_sel:[1,0,0]
	v_pk_fma_f32 v[44:45], v[58:59], v[112:113], v[44:45] op_sel:[1,0,0]
	v_pk_fma_f32 v[46:47], v[58:59], v[114:115], v[46:47] op_sel:[1,0,0]
	v_pk_fma_f32 v[48:49], v[58:59], v[116:117], v[48:49] op_sel:[1,0,0]
	v_pk_fma_f32 v[50:51], v[58:59], v[118:119], v[50:51] op_sel:[1,0,0]
	v_pk_fma_f32 v[36:37], v[58:59], v[120:121], v[36:37] op_sel:[1,0,0]
	ds_read_b128 v[106:109], v57 offset:192
	ds_read_b128 v[110:113], v57 offset:208
	ds_read_b128 v[114:117], v57 offset:224
	ds_read_b128 v[118:121], v57 offset:240
	s_waitcnt vmcnt(61) lgkmcnt(4)
	v_pk_fma_f32 v[38:39], v[60:61], v[90:91], v[38:39] op_sel_hi:[0,1,1]
	v_pk_fma_f32 v[40:41], v[60:61], v[92:93], v[40:41] op_sel_hi:[0,1,1]
	v_pk_fma_f32 v[42:43], v[60:61], v[94:95], v[42:43] op_sel_hi:[0,1,1]
	v_pk_fma_f32 v[44:45], v[60:61], v[96:97], v[44:45] op_sel_hi:[0,1,1]
	v_pk_fma_f32 v[46:47], v[60:61], v[98:99], v[46:47] op_sel_hi:[0,1,1]
	v_pk_fma_f32 v[48:49], v[60:61], v[100:101], v[48:49] op_sel_hi:[0,1,1]
	v_pk_fma_f32 v[50:51], v[60:61], v[102:103], v[50:51] op_sel_hi:[0,1,1]
	v_pk_fma_f32 v[36:37], v[60:61], v[104:105], v[36:37] op_sel_hi:[0,1,1]
	ds_read_b128 v[90:93], v57 offset:256
	ds_read_b128 v[94:97], v57 offset:272
	ds_read_b128 v[98:101], v57 offset:288
	ds_read_b128 v[102:105], v57 offset:304
	s_waitcnt vmcnt(60) lgkmcnt(4)
	v_pk_fma_f32 v[38:39], v[60:61], v[106:107], v[38:39] op_sel:[1,0,0]
	v_pk_fma_f32 v[40:41], v[60:61], v[108:109], v[40:41] op_sel:[1,0,0]
	v_pk_fma_f32 v[42:43], v[60:61], v[110:111], v[42:43] op_sel:[1,0,0]
	v_pk_fma_f32 v[44:45], v[60:61], v[112:113], v[44:45] op_sel:[1,0,0]
	v_pk_fma_f32 v[46:47], v[60:61], v[114:115], v[46:47] op_sel:[1,0,0]
	v_pk_fma_f32 v[48:49], v[60:61], v[116:117], v[48:49] op_sel:[1,0,0]
	v_pk_fma_f32 v[50:51], v[60:61], v[118:119], v[50:51] op_sel:[1,0,0]
	v_pk_fma_f32 v[36:37], v[60:61], v[120:121], v[36:37] op_sel:[1,0,0]
	ds_read_b128 v[106:109], v57 offset:320
	ds_read_b128 v[110:113], v57 offset:336
	ds_read_b128 v[114:117], v57 offset:352
	ds_read_b128 v[118:121], v57 offset:368
	s_waitcnt vmcnt(59) lgkmcnt(4)
	v_pk_fma_f32 v[38:39], v[62:63], v[90:91], v[38:39] op_sel_hi:[0,1,1]
	v_pk_fma_f32 v[40:41], v[62:63], v[92:93], v[40:41] op_sel_hi:[0,1,1]
	v_pk_fma_f32 v[42:43], v[62:63], v[94:95], v[42:43] op_sel_hi:[0,1,1]
	v_pk_fma_f32 v[44:45], v[62:63], v[96:97], v[44:45] op_sel_hi:[0,1,1]
	v_pk_fma_f32 v[46:47], v[62:63], v[98:99], v[46:47] op_sel_hi:[0,1,1]
	v_pk_fma_f32 v[48:49], v[62:63], v[100:101], v[48:49] op_sel_hi:[0,1,1]
	v_pk_fma_f32 v[50:51], v[62:63], v[102:103], v[50:51] op_sel_hi:[0,1,1]
	v_pk_fma_f32 v[36:37], v[62:63], v[104:105], v[36:37] op_sel_hi:[0,1,1]
	ds_read_b128 v[90:93], v57 offset:384
	ds_read_b128 v[94:97], v57 offset:400
	ds_read_b128 v[98:101], v57 offset:416
	ds_read_b128 v[102:105], v57 offset:432
	s_waitcnt vmcnt(58) lgkmcnt(4)
; #define LAS __attribute__((address_space(3)))
; __device__ __forceinline__ void phase_prep(const Args& a, LAS unsigned char* lds) {
;     ...
;             const int kbeg = wave * 128;
; #pragma unroll 8
;             for (int k = kbeg; k < kbeg + 128; ++k) { const float wv = w[(size_t)k * 6144];
;                 const LAS f32x4* s4 = (const LAS f32x4*)(sc + k * 16);
; #pragma unroll
;                 for (int q = 0; q < 4; ++q) { const f32x4 s = s4[q]; acc[4 * q] += s[0] * wv; acc[4 * q + 1] += s[1] * wv; acc[4 * q + 2] += s[2] * wv; acc[4 * q + 3] += s[3] * wv; } }
	v_pk_fma_f32 v[38:39], v[62:63], v[106:107], v[38:39] op_sel:[1,0,0]
	v_pk_fma_f32 v[40:41], v[62:63], v[108:109], v[40:41] op_sel:[1,0,0]
	v_pk_fma_f32 v[42:43], v[62:63], v[110:111], v[42:43] op_sel:[1,0,0]
	v_pk_fma_f32 v[44:45], v[62:63], v[112:113], v[44:45] op_sel:[1,0,0]
	v_pk_fma_f32 v[46:47], v[62:63], v[114:115], v[46:47] op_sel:[1,0,0]
	v_pk_fma_f32 v[48:49], v[62:63], v[116:117], v[48:49] op_sel:[1,0,0]
	v_pk_fma_f32 v[50:51], v[62:63], v[118:119], v[50:51] op_sel:[1,0,0]
	v_pk_fma_f32 v[36:37], v[62:63], v[120:121], v[36:37] op_sel:[1,0,0]
	ds_read_b128 v[106:109], v57 offset:448
	ds_read_b128 v[110:113], v57 offset:464
	ds_read_b128 v[114:117], v57 offset:480
	ds_read_b128 v[118:121], v57 offset:496
	s_waitcnt vmcnt(57) lgkmcnt(4)
	v_pk_fma_f32 v[38:39], v[64:65], v[90:91], v[38:39] op_sel_hi:[0,1,1]
	v_pk_fma_f32 v[40:41], v[64:65], v[92:93], v[40:41] op_sel_hi:[0,1,1]
	v_pk_fma_f32 v[42:43], v[64:65], v[94:95], v[42:43] op_sel_hi:[0,1,1]
	v_pk_fma_f32 v[44:45], v[64:65], v[96:97], v[44:45] op_sel_hi:[0,1,1]
	v_pk_fma_f32 v[46:47], v[64:65], v[98:99], v[46:47] op_sel_hi:[0,1,1]
	v_pk_fma_f32 v[48:49], v[64:65], v[100:101], v[48:49] op_sel_hi:[0,1,1]
	v_pk_fma_f32 v[50:51], v[64:65], v[102:103], v[50:51] op_sel_hi:[0,1,1]
	v_pk_fma_f32 v[36:37], v[64:65], v[104:105], v[36:37] op_sel_hi:[0,1,1]
	ds_read_b128 v[90:93], v57 offset:512
	ds_read_b128 v[94:97], v57 offset:528
	ds_read_b128 v[98:101], v57 offset:544
	ds_read_b128 v[102:105], v57 offset:560
	s_waitcnt vmcnt(56) lgkmcnt(4)
	v_pk_fma_f32 v[38:39], v[64:65], v[106:107], v[38:39] op_sel:[1,0,0]
	v_pk_fma_f32 v[40:41], v[64:65], v[108:109], v[40:41] op_sel:[1,0,0]
	v_pk_fma_f32 v[42:43], v[64:65], v[110:111], v[42:43] op_sel:[1,0,0]
	v_pk_fma_f32 v[44:45], v[64:65], v[112:113], v[44:45] op_sel:[1,0,0]
	v_pk_fma_f32 v[46:47], v[64:65], v[114:115], v[46:47] op_sel:[1,0,0]
	v_pk_fma_f32 v[48:49], v[64:65], v[116:117], v[48:49] op_sel:[1,0,0]
	v_pk_fma_f32 v[50:51], v[64:65], v[118:119], v[50:51] op_sel:[1,0,0]
	v_pk_fma_f32 v[36:37], v[64:65], v[120:121], v[36:37] op_sel:[1,0,0]
	ds_read_b128 v[106:109], v57 offset:576
	ds_read_b128 v[110:113], v57 offset:592
	ds_read_b128 v[114:117], v57 offset:608
	ds_read_b128 v[118:121], v57 offset:624
	s_waitcnt vmcnt(55) lgkmcnt(4)
	v_pk_fma_f32 v[38:39], v[66:67], v[90:91], v[38:39] op_sel_hi:[0,1,1]
	v_pk_fma_f32 v[40:41], v[66:67], v[92:93], v[40:41] op_sel_hi:[0,1,1]
	v_pk_fma_f32 v[42:43], v[66:67], v[94:95], v[42:43] op_sel_hi:[0,1,1]
	v_pk_fma_f32 v[44:45], v[66:67], v[96:97], v[44:45] op_sel_hi:[0,1,1]
	v_pk_fma_f32 v[46:47], v[66:67], v[98:99], v[46:47] op_sel_hi:[0,1,1]
	v_pk_fma_f32 v[48:49], v[66:67], v[100:101], v[48:49] op_sel_hi:[0,1,1]
	v_pk_fma_f32 v[50:51], v[66:67], v[102:103], v[50:51] op_sel_hi:[0,1,1]
	v_pk_fma_f32 v[36:37], v[66:67], v[104:105], v[36:37] op_sel_hi:[0,1,1]
	ds_read_b128 v[90:93], v57 offset:640
	ds_read_b128 v[94:97], v57 offset:656
	ds_read_b128 v[98:101], v57 offset:672
	ds_read_b128 v[102:105], v57 offset:688
	s_waitcnt vmcnt(54) lgkmcnt(4)
	v_pk_fma_f32 v[38:39], v[66:67], v[106:107], v[38:39] op_sel:[1,0,0]
	v_pk_fma_f32 v[40:41], v[66:67], v[108:109], v[40:41] op_sel:[1,0,0]
	v_pk_fma_f32 v[42:43], v[66:67], v[110:111], v[42:43] op_sel:[1,0,0]
	v_pk_fma_f32 v[44:45], v[66:67], v[112:113], v[44:45] op_sel:[1,0,0]
	v_pk_fma_f32 v[46:47], v[66:67], v[114:115], v[46:47] op_sel:[1,0,0]
	v_pk_fma_f32 v[48:49], v[66:67], v[116:117], v[48:49] op_sel:[1,0,0]
	v_pk_fma_f32 v[50:51], v[66:67], v[118:119], v[50:51] op_sel:[1,0,0]
	v_pk_fma_f32 v[36:37], v[66:67], v[120:121], v[36:37] op_sel:[1,0,0]
	ds_read_b128 v[106:109], v57 offset:704
	ds_read_b128 v[110:113], v57 offset:720
	ds_read_b128 v[114:117], v57 offset:736
	ds_read_b128 v[118:121], v57 offset:752
	s_waitcnt vmcnt(53) lgkmcnt(4)
	v_pk_fma_f32 v[38:39], v[68:69], v[90:91], v[38:39] op_sel_hi:[0,1,1]
	v_pk_fma_f32 v[40:41], v[68:69], v[92:93], v[40:41] op_sel_hi:[0,1,1]
	v_pk_fma_f32 v[42:43], v[68:69], v[94:95], v[42:43] op_sel_hi:[0,1,1]
	v_pk_fma_f32 v[44:45], v[68:69], v[96:97], v[44:45] op_sel_hi:[0,1,1]
	v_pk_fma_f32 v[46:47], v[68:69], v[98:99], v[46:47] op_sel_hi:[0,1,1]
	v_pk_fma_f32 v[48:49], v[68:69], v[100:101], v[48:49] op_sel_hi:[0,1,1]
	v_pk_fma_f32 v[50:51], v[68:69], v[102:103], v[50:51] op_sel_hi:[0,1,1]
	v_pk_fma_f32 v[36:37], v[68:69], v[104:105], v[36:37] op_sel_hi:[0,1,1]
	ds_read_b128 v[90:93], v57 offset:768
	ds_read_b128 v[94:97], v57 offset:784
	ds_read_b128 v[98:101], v57 offset:800
	ds_read_b128 v[102:105], v57 offset:816
	s_waitcnt vmcnt(52) lgkmcnt(4)
	v_pk_fma_f32 v[38:39], v[68:69], v[106:107], v[38:39] op_sel:[1,0,0]
	v_pk_fma_f32 v[40:41], v[68:69], v[108:109], v[40:41] op_sel:[1,0,0]
	v_pk_fma_f32 v[42:43], v[68:69], v[110:111], v[42:43] op_sel:[1,0,0]
	v_pk_fma_f32 v[44:45], v[68:69], v[112:113], v[44:45] op_sel:[1,0,0]
	v_pk_fma_f32 v[46:47], v[68:69], v[114:115], v[46:47] op_sel:[1,0,0]
	v_pk_fma_f32 v[48:49], v[68:69], v[116:117], v[48:49] op_sel:[1,0,0]
	v_pk_fma_f32 v[50:51], v[68:69], v[118:119], v[50:51] op_sel:[1,0,0]
	v_pk_fma_f32 v[36:37], v[68:69], v[120:121], v[36:37] op_sel:[1,0,0]
	ds_read_b128 v[106:109], v57 offset:832
	ds_read_b128 v[110:113], v57 offset:848
	ds_read_b128 v[114:117], v57 offset:864
	ds_read_b128 v[118:121], v57 offset:880
	s_waitcnt vmcnt(51) lgkmcnt(4)
; #define LAS __attribute__((address_space(3)))
; __device__ __forceinline__ void phase_prep(const Args& a, LAS unsigned char* lds) {
;     ...
;             const int kbeg = wave * 128;
; #pragma unroll 8
;             for (int k = kbeg; k < kbeg + 128; ++k) { const float wv = w[(size_t)k * 6144];
;                 const LAS f32x4* s4 = (const LAS f32x4*)(sc + k * 16);
; #pragma unroll
;                 for (int q = 0; q < 4; ++q) { const f32x4 s = s4[q]; acc[4 * q] += s[0] * wv; acc[4 * q + 1] += s[1] * wv; acc[4 * q + 2] += s[2] * wv; acc[4 * q + 3] += s[3] * wv; } }
	v_pk_fma_f32 v[38:39], v[70:71], v[90:91], v[38:39] op_sel_hi:[0,1,1]
	v_pk_fma_f32 v[40:41], v[70:71], v[92:93], v[40:41] op_sel_hi:[0,1,1]
	v_pk_fma_f32 v[42:43], v[70:71], v[94:95], v[42:43] op_sel_hi:[0,1,1]
	v_pk_fma_f32 v[44:45], v[70:71], v[96:97], v[44:45] op_sel_hi:[0,1,1]
	v_pk_fma_f32 v[46:47], v[70:71], v[98:99], v[46:47] op_sel_hi:[0,1,1]
	v_pk_fma_f32 v[48:49], v[70:71], v[100:101], v[48:49] op_sel_hi:[0,1,1]
	v_pk_fma_f32 v[50:51], v[70:71], v[102:103], v[50:51] op_sel_hi:[0,1,1]
	v_pk_fma_f32 v[36:37], v[70:71], v[104:105], v[36:37] op_sel_hi:[0,1,1]
	ds_read_b128 v[90:93], v57 offset:896
	ds_read_b128 v[94:97], v57 offset:912
	ds_read_b128 v[98:101], v57 offset:928
	ds_read_b128 v[102:105], v57 offset:944
	s_waitcnt vmcnt(50) lgkmcnt(4)
	v_pk_fma_f32 v[38:39], v[70:71], v[106:107], v[38:39] op_sel:[1,0,0]
	v_pk_fma_f32 v[40:41], v[70:71], v[108:109], v[40:41] op_sel:[1,0,0]
	v_pk_fma_f32 v[42:43], v[70:71], v[110:111], v[42:43] op_sel:[1,0,0]
	v_pk_fma_f32 v[44:45], v[70:71], v[112:113], v[44:45] op_sel:[1,0,0]
	v_pk_fma_f32 v[46:47], v[70:71], v[114:115], v[46:47] op_sel:[1,0,0]
	v_pk_fma_f32 v[48:49], v[70:71], v[116:117], v[48:49] op_sel:[1,0,0]
	v_pk_fma_f32 v[50:51], v[70:71], v[118:119], v[50:51] op_sel:[1,0,0]
	v_pk_fma_f32 v[36:37], v[70:71], v[120:121], v[36:37] op_sel:[1,0,0]
	ds_read_b128 v[106:109], v57 offset:960
	ds_read_b128 v[110:113], v57 offset:976
	ds_read_b128 v[114:117], v57 offset:992
	ds_read_b128 v[118:121], v57 offset:1008
	s_waitcnt vmcnt(49) lgkmcnt(4)
	v_pk_fma_f32 v[38:39], v[72:73], v[90:91], v[38:39] op_sel_hi:[0,1,1]
	v_pk_fma_f32 v[40:41], v[72:73], v[92:93], v[40:41] op_sel_hi:[0,1,1]
	v_pk_fma_f32 v[42:43], v[72:73], v[94:95], v[42:43] op_sel_hi:[0,1,1]
	v_pk_fma_f32 v[44:45], v[72:73], v[96:97], v[44:45] op_sel_hi:[0,1,1]
	v_pk_fma_f32 v[46:47], v[72:73], v[98:99], v[46:47] op_sel_hi:[0,1,1]
	v_pk_fma_f32 v[48:49], v[72:73], v[100:101], v[48:49] op_sel_hi:[0,1,1]
	v_pk_fma_f32 v[50:51], v[72:73], v[102:103], v[50:51] op_sel_hi:[0,1,1]
	v_pk_fma_f32 v[36:37], v[72:73], v[104:105], v[36:37] op_sel_hi:[0,1,1]
	ds_read_b128 v[90:93], v57 offset:1024
	ds_read_b128 v[94:97], v57 offset:1040
	ds_read_b128 v[98:101], v57 offset:1056
	ds_read_b128 v[102:105], v57 offset:1072
	s_waitcnt vmcnt(48) lgkmcnt(4)
	v_pk_fma_f32 v[38:39], v[72:73], v[106:107], v[38:39] op_sel:[1,0,0]
	v_pk_fma_f32 v[40:41], v[72:73], v[108:109], v[40:41] op_sel:[1,0,0]
	v_pk_fma_f32 v[42:43], v[72:73], v[110:111], v[42:43] op_sel:[1,0,0]
	v_pk_fma_f32 v[44:45], v[72:73], v[112:113], v[44:45] op_sel:[1,0,0]
	v_pk_fma_f32 v[46:47], v[72:73], v[114:115], v[46:47] op_sel:[1,0,0]
	v_pk_fma_f32 v[48:49], v[72:73], v[116:117], v[48:49] op_sel:[1,0,0]
	v_pk_fma_f32 v[50:51], v[72:73], v[118:119], v[50:51] op_sel:[1,0,0]
	v_pk_fma_f32 v[36:37], v[72:73], v[120:121], v[36:37] op_sel:[1,0,0]
	ds_read_b128 v[106:109], v57 offset:1088
	ds_read_b128 v[110:113], v57 offset:1104
	ds_read_b128 v[114:117], v57 offset:1120
	ds_read_b128 v[118:121], v57 offset:1136
	s_waitcnt vmcnt(47) lgkmcnt(4)
	v_pk_fma_f32 v[38:39], v[74:75], v[90:91], v[38:39] op_sel_hi:[0,1,1]
	v_pk_fma_f32 v[40:41], v[74:75], v[92:93], v[40:41] op_sel_hi:[0,1,1]
	v_pk_fma_f32 v[42:43], v[74:75], v[94:95], v[42:43] op_sel_hi:[0,1,1]
	v_pk_fma_f32 v[44:45], v[74:75], v[96:97], v[44:45] op_sel_hi:[0,1,1]
	v_pk_fma_f32 v[46:47], v[74:75], v[98:99], v[46:47] op_sel_hi:[0,1,1]
	v_pk_fma_f32 v[48:49], v[74:75], v[100:101], v[48:49] op_sel_hi:[0,1,1]
	v_pk_fma_f32 v[50:51], v[74:75], v[102:103], v[50:51] op_sel_hi:[0,1,1]
	v_pk_fma_f32 v[36:37], v[74:75], v[104:105], v[36:37] op_sel_hi:[0,1,1]
	ds_read_b128 v[90:93], v57 offset:1152
	ds_read_b128 v[94:97], v57 offset:1168
	ds_read_b128 v[98:101], v57 offset:1184
	ds_read_b128 v[102:105], v57 offset:1200
	s_waitcnt vmcnt(46) lgkmcnt(4)
	v_pk_fma_f32 v[38:39], v[74:75], v[106:107], v[38:39] op_sel:[1,0,0]
	v_pk_fma_f32 v[40:41], v[74:75], v[108:109], v[40:41] op_sel:[1,0,0]
	v_pk_fma_f32 v[42:43], v[74:75], v[110:111], v[42:43] op_sel:[1,0,0]
	v_pk_fma_f32 v[44:45], v[74:75], v[112:113], v[44:45] op_sel:[1,0,0]
	v_pk_fma_f32 v[46:47], v[74:75], v[114:115], v[46:47] op_sel:[1,0,0]
	v_pk_fma_f32 v[48:49], v[74:75], v[116:117], v[48:49] op_sel:[1,0,0]
	v_pk_fma_f32 v[50:51], v[74:75], v[118:119], v[50:51] op_sel:[1,0,0]
	v_pk_fma_f32 v[36:37], v[74:75], v[120:121], v[36:37] op_sel:[1,0,0]
	ds_read_b128 v[106:109], v57 offset:1216
	ds_read_b128 v[110:113], v57 offset:1232
	ds_read_b128 v[114:117], v57 offset:1248
	ds_read_b128 v[118:121], v57 offset:1264
	s_waitcnt vmcnt(45) lgkmcnt(4)
	v_pk_fma_f32 v[38:39], v[76:77], v[90:91], v[38:39] op_sel_hi:[0,1,1]
	v_pk_fma_f32 v[40:41], v[76:77], v[92:93], v[40:41] op_sel_hi:[0,1,1]
	v_pk_fma_f32 v[42:43], v[76:77], v[94:95], v[42:43] op_sel_hi:[0,1,1]
	v_pk_fma_f32 v[44:45], v[76:77], v[96:97], v[44:45] op_sel_hi:[0,1,1]
	v_pk_fma_f32 v[46:47], v[76:77], v[98:99], v[46:47] op_sel_hi:[0,1,1]
	v_pk_fma_f32 v[48:49], v[76:77], v[100:101], v[48:49] op_sel_hi:[0,1,1]
	v_pk_fma_f32 v[50:51], v[76:77], v[102:103], v[50:51] op_sel_hi:[0,1,1]
	v_pk_fma_f32 v[36:37], v[76:77], v[104:105], v[36:37] op_sel_hi:[0,1,1]
	ds_read_b128 v[90:93], v57 offset:1280
	ds_read_b128 v[94:97], v57 offset:1296
	ds_read_b128 v[98:101], v57 offset:1312
	ds_read_b128 v[102:105], v57 offset:1328
	s_waitcnt vmcnt(44) lgkmcnt(4)
; #define LAS __attribute__((address_space(3)))
; __device__ __forceinline__ void phase_prep(const Args& a, LAS unsigned char* lds) {
;     ...
;             const int kbeg = wave * 128;
; #pragma unroll 8
;             for (int k = kbeg; k < kbeg + 128; ++k) { const float wv = w[(size_t)k * 6144];
;                 const LAS f32x4* s4 = (const LAS f32x4*)(sc + k * 16);
; #pragma unroll
;                 for (int q = 0; q < 4; ++q) { const f32x4 s = s4[q]; acc[4 * q] += s[0] * wv; acc[4 * q + 1] += s[1] * wv; acc[4 * q + 2] += s[2] * wv; acc[4 * q + 3] += s[3] * wv; } }
	v_pk_fma_f32 v[38:39], v[76:77], v[106:107], v[38:39] op_sel:[1,0,0]
	v_pk_fma_f32 v[40:41], v[76:77], v[108:109], v[40:41] op_sel:[1,0,0]
	v_pk_fma_f32 v[42:43], v[76:77], v[110:111], v[42:43] op_sel:[1,0,0]
	v_pk_fma_f32 v[44:45], v[76:77], v[112:113], v[44:45] op_sel:[1,0,0]
	v_pk_fma_f32 v[46:47], v[76:77], v[114:115], v[46:47] op_sel:[1,0,0]
	v_pk_fma_f32 v[48:49], v[76:77], v[116:117], v[48:49] op_sel:[1,0,0]
	v_pk_fma_f32 v[50:51], v[76:77], v[118:119], v[50:51] op_sel:[1,0,0]
	v_pk_fma_f32 v[36:37], v[76:77], v[120:121], v[36:37] op_sel:[1,0,0]
	ds_read_b128 v[106:109], v57 offset:1344
	ds_read_b128 v[110:113], v57 offset:1360
	ds_read_b128 v[114:117], v57 offset:1376
	ds_read_b128 v[118:121], v57 offset:1392
	s_waitcnt vmcnt(43) lgkmcnt(4)
	v_pk_fma_f32 v[38:39], v[78:79], v[90:91], v[38:39] op_sel_hi:[0,1,1]
	v_pk_fma_f32 v[40:41], v[78:79], v[92:93], v[40:41] op_sel_hi:[0,1,1]
	v_pk_fma_f32 v[42:43], v[78:79], v[94:95], v[42:43] op_sel_hi:[0,1,1]
	v_pk_fma_f32 v[44:45], v[78:79], v[96:97], v[44:45] op_sel_hi:[0,1,1]
	v_pk_fma_f32 v[46:47], v[78:79], v[98:99], v[46:47] op_sel_hi:[0,1,1]
	v_pk_fma_f32 v[48:49], v[78:79], v[100:101], v[48:49] op_sel_hi:[0,1,1]
	v_pk_fma_f32 v[50:51], v[78:79], v[102:103], v[50:51] op_sel_hi:[0,1,1]
	v_pk_fma_f32 v[36:37], v[78:79], v[104:105], v[36:37] op_sel_hi:[0,1,1]
	ds_read_b128 v[90:93], v57 offset:1408
	ds_read_b128 v[94:97], v57 offset:1424
	ds_read_b128 v[98:101], v57 offset:1440
	ds_read_b128 v[102:105], v57 offset:1456
	s_waitcnt vmcnt(42) lgkmcnt(4)
	v_pk_fma_f32 v[38:39], v[78:79], v[106:107], v[38:39] op_sel:[1,0,0]
	v_pk_fma_f32 v[40:41], v[78:79], v[108:109], v[40:41] op_sel:[1,0,0]
	v_pk_fma_f32 v[42:43], v[78:79], v[110:111], v[42:43] op_sel:[1,0,0]
	v_pk_fma_f32 v[44:45], v[78:79], v[112:113], v[44:45] op_sel:[1,0,0]
	v_pk_fma_f32 v[46:47], v[78:79], v[114:115], v[46:47] op_sel:[1,0,0]
	v_pk_fma_f32 v[48:49], v[78:79], v[116:117], v[48:49] op_sel:[1,0,0]
	v_pk_fma_f32 v[50:51], v[78:79], v[118:119], v[50:51] op_sel:[1,0,0]
	v_pk_fma_f32 v[36:37], v[78:79], v[120:121], v[36:37] op_sel:[1,0,0]
	ds_read_b128 v[106:109], v57 offset:1472
	ds_read_b128 v[110:113], v57 offset:1488
	ds_read_b128 v[114:117], v57 offset:1504
	ds_read_b128 v[118:121], v57 offset:1520
	s_waitcnt vmcnt(41) lgkmcnt(4)
	v_pk_fma_f32 v[38:39], v[80:81], v[90:91], v[38:39] op_sel_hi:[0,1,1]
	v_pk_fma_f32 v[40:41], v[80:81], v[92:93], v[40:41] op_sel_hi:[0,1,1]
	v_pk_fma_f32 v[42:43], v[80:81], v[94:95], v[42:43] op_sel_hi:[0,1,1]
	v_pk_fma_f32 v[44:45], v[80:81], v[96:97], v[44:45] op_sel_hi:[0,1,1]
	v_pk_fma_f32 v[46:47], v[80:81], v[98:99], v[46:47] op_sel_hi:[0,1,1]
	v_pk_fma_f32 v[48:49], v[80:81], v[100:101], v[48:49] op_sel_hi:[0,1,1]
	v_pk_fma_f32 v[50:51], v[80:81], v[102:103], v[50:51] op_sel_hi:[0,1,1]
	v_pk_fma_f32 v[36:37], v[80:81], v[104:105], v[36:37] op_sel_hi:[0,1,1]
	ds_read_b128 v[90:93], v57 offset:1536
	ds_read_b128 v[94:97], v57 offset:1552
	ds_read_b128 v[98:101], v57 offset:1568
	ds_read_b128 v[102:105], v57 offset:1584
	s_waitcnt vmcnt(40) lgkmcnt(4)
	v_pk_fma_f32 v[38:39], v[80:81], v[106:107], v[38:39] op_sel:[1,0,0]
	v_pk_fma_f32 v[40:41], v[80:81], v[108:109], v[40:41] op_sel:[1,0,0]
	v_pk_fma_f32 v[42:43], v[80:81], v[110:111], v[42:43] op_sel:[1,0,0]
	v_pk_fma_f32 v[44:45], v[80:81], v[112:113], v[44:45] op_sel:[1,0,0]
	v_pk_fma_f32 v[46:47], v[80:81], v[114:115], v[46:47] op_sel:[1,0,0]
	v_pk_fma_f32 v[48:49], v[80:81], v[116:117], v[48:49] op_sel:[1,0,0]
	v_pk_fma_f32 v[50:51], v[80:81], v[118:119], v[50:51] op_sel:[1,0,0]
	v_pk_fma_f32 v[36:37], v[80:81], v[120:121], v[36:37] op_sel:[1,0,0]
	ds_read_b128 v[106:109], v57 offset:1600
	ds_read_b128 v[110:113], v57 offset:1616
	ds_read_b128 v[114:117], v57 offset:1632
	ds_read_b128 v[118:121], v57 offset:1648
	s_waitcnt vmcnt(39) lgkmcnt(4)
	v_pk_fma_f32 v[38:39], v[82:83], v[90:91], v[38:39] op_sel_hi:[0,1,1]
	v_pk_fma_f32 v[40:41], v[82:83], v[92:93], v[40:41] op_sel_hi:[0,1,1]
	v_pk_fma_f32 v[42:43], v[82:83], v[94:95], v[42:43] op_sel_hi:[0,1,1]
	v_pk_fma_f32 v[44:45], v[82:83], v[96:97], v[44:45] op_sel_hi:[0,1,1]
	v_pk_fma_f32 v[46:47], v[82:83], v[98:99], v[46:47] op_sel_hi:[0,1,1]
	v_pk_fma_f32 v[48:49], v[82:83], v[100:101], v[48:49] op_sel_hi:[0,1,1]
	v_pk_fma_f32 v[50:51], v[82:83], v[102:103], v[50:51] op_sel_hi:[0,1,1]
	v_pk_fma_f32 v[36:37], v[82:83], v[104:105], v[36:37] op_sel_hi:[0,1,1]
	ds_read_b128 v[90:93], v57 offset:1664
	ds_read_b128 v[94:97], v57 offset:1680
	ds_read_b128 v[98:101], v57 offset:1696
	ds_read_b128 v[102:105], v57 offset:1712
	s_waitcnt vmcnt(38) lgkmcnt(4)
	v_pk_fma_f32 v[38:39], v[82:83], v[106:107], v[38:39] op_sel:[1,0,0]
	v_pk_fma_f32 v[40:41], v[82:83], v[108:109], v[40:41] op_sel:[1,0,0]
	v_pk_fma_f32 v[42:43], v[82:83], v[110:111], v[42:43] op_sel:[1,0,0]
	v_pk_fma_f32 v[44:45], v[82:83], v[112:113], v[44:45] op_sel:[1,0,0]
	v_pk_fma_f32 v[46:47], v[82:83], v[114:115], v[46:47] op_sel:[1,0,0]
	v_pk_fma_f32 v[48:49], v[82:83], v[116:117], v[48:49] op_sel:[1,0,0]
	v_pk_fma_f32 v[50:51], v[82:83], v[118:119], v[50:51] op_sel:[1,0,0]
	v_pk_fma_f32 v[36:37], v[82:83], v[120:121], v[36:37] op_sel:[1,0,0]
	ds_read_b128 v[106:109], v57 offset:1728
	ds_read_b128 v[110:113], v57 offset:1744
	ds_read_b128 v[114:117], v57 offset:1760
	ds_read_b128 v[118:121], v57 offset:1776
	s_waitcnt vmcnt(37) lgkmcnt(4)
; #define LAS __attribute__((address_space(3)))
; __device__ __forceinline__ void phase_prep(const Args& a, LAS unsigned char* lds) {
;     ...
;             const int kbeg = wave * 128;
; #pragma unroll 8
;             for (int k = kbeg; k < kbeg + 128; ++k) { const float wv = w[(size_t)k * 6144];
;                 const LAS f32x4* s4 = (const LAS f32x4*)(sc + k * 16);
; #pragma unroll
;                 for (int q = 0; q < 4; ++q) { const f32x4 s = s4[q]; acc[4 * q] += s[0] * wv; acc[4 * q + 1] += s[1] * wv; acc[4 * q + 2] += s[2] * wv; acc[4 * q + 3] += s[3] * wv; } }
	v_pk_fma_f32 v[38:39], v[84:85], v[90:91], v[38:39] op_sel_hi:[0,1,1]
	v_pk_fma_f32 v[40:41], v[84:85], v[92:93], v[40:41] op_sel_hi:[0,1,1]
	v_pk_fma_f32 v[42:43], v[84:85], v[94:95], v[42:43] op_sel_hi:[0,1,1]
	v_pk_fma_f32 v[44:45], v[84:85], v[96:97], v[44:45] op_sel_hi:[0,1,1]
	v_pk_fma_f32 v[46:47], v[84:85], v[98:99], v[46:47] op_sel_hi:[0,1,1]
	v_pk_fma_f32 v[48:49], v[84:85], v[100:101], v[48:49] op_sel_hi:[0,1,1]
	v_pk_fma_f32 v[50:51], v[84:85], v[102:103], v[50:51] op_sel_hi:[0,1,1]
	v_pk_fma_f32 v[36:37], v[84:85], v[104:105], v[36:37] op_sel_hi:[0,1,1]
	ds_read_b128 v[90:93], v57 offset:1792
	ds_read_b128 v[94:97], v57 offset:1808
	ds_read_b128 v[98:101], v57 offset:1824
	ds_read_b128 v[102:105], v57 offset:1840
	s_waitcnt vmcnt(36) lgkmcnt(4)
	v_pk_fma_f32 v[38:39], v[84:85], v[106:107], v[38:39] op_sel:[1,0,0]
	v_pk_fma_f32 v[40:41], v[84:85], v[108:109], v[40:41] op_sel:[1,0,0]
	v_pk_fma_f32 v[42:43], v[84:85], v[110:111], v[42:43] op_sel:[1,0,0]
	v_pk_fma_f32 v[44:45], v[84:85], v[112:113], v[44:45] op_sel:[1,0,0]
	v_pk_fma_f32 v[46:47], v[84:85], v[114:115], v[46:47] op_sel:[1,0,0]
	v_pk_fma_f32 v[48:49], v[84:85], v[116:117], v[48:49] op_sel:[1,0,0]
	v_pk_fma_f32 v[50:51], v[84:85], v[118:119], v[50:51] op_sel:[1,0,0]
	v_pk_fma_f32 v[36:37], v[84:85], v[120:121], v[36:37] op_sel:[1,0,0]
	ds_read_b128 v[106:109], v57 offset:1856
	ds_read_b128 v[110:113], v57 offset:1872
	ds_read_b128 v[114:117], v57 offset:1888
	ds_read_b128 v[118:121], v57 offset:1904
	s_waitcnt vmcnt(35) lgkmcnt(4)
	v_pk_fma_f32 v[38:39], v[86:87], v[90:91], v[38:39] op_sel_hi:[0,1,1]
	v_pk_fma_f32 v[40:41], v[86:87], v[92:93], v[40:41] op_sel_hi:[0,1,1]
	v_pk_fma_f32 v[42:43], v[86:87], v[94:95], v[42:43] op_sel_hi:[0,1,1]
	v_pk_fma_f32 v[44:45], v[86:87], v[96:97], v[44:45] op_sel_hi:[0,1,1]
	v_pk_fma_f32 v[46:47], v[86:87], v[98:99], v[46:47] op_sel_hi:[0,1,1]
	v_pk_fma_f32 v[48:49], v[86:87], v[100:101], v[48:49] op_sel_hi:[0,1,1]
	v_pk_fma_f32 v[50:51], v[86:87], v[102:103], v[50:51] op_sel_hi:[0,1,1]
	v_pk_fma_f32 v[36:37], v[86:87], v[104:105], v[36:37] op_sel_hi:[0,1,1]
	ds_read_b128 v[90:93], v57 offset:1920
	ds_read_b128 v[94:97], v57 offset:1936
	ds_read_b128 v[98:101], v57 offset:1952
	ds_read_b128 v[102:105], v57 offset:1968
	s_waitcnt vmcnt(34) lgkmcnt(4)
	v_pk_fma_f32 v[38:39], v[86:87], v[106:107], v[38:39] op_sel:[1,0,0]
	v_pk_fma_f32 v[40:41], v[86:87], v[108:109], v[40:41] op_sel:[1,0,0]
	v_pk_fma_f32 v[42:43], v[86:87], v[110:111], v[42:43] op_sel:[1,0,0]
	v_pk_fma_f32 v[44:45], v[86:87], v[112:113], v[44:45] op_sel:[1,0,0]
	v_pk_fma_f32 v[46:47], v[86:87], v[114:115], v[46:47] op_sel:[1,0,0]
	v_pk_fma_f32 v[48:49], v[86:87], v[116:117], v[48:49] op_sel:[1,0,0]
	v_pk_fma_f32 v[50:51], v[86:87], v[118:119], v[50:51] op_sel:[1,0,0]
	v_pk_fma_f32 v[36:37], v[86:87], v[120:121], v[36:37] op_sel:[1,0,0]
	ds_read_b128 v[106:109], v57 offset:1984
	ds_read_b128 v[110:113], v57 offset:2000
	ds_read_b128 v[114:117], v57 offset:2016
	ds_read_b128 v[118:121], v57 offset:2032
	s_waitcnt vmcnt(33) lgkmcnt(4)
	v_pk_fma_f32 v[38:39], v[88:89], v[90:91], v[38:39] op_sel_hi:[0,1,1]
	v_pk_fma_f32 v[40:41], v[88:89], v[92:93], v[40:41] op_sel_hi:[0,1,1]
	v_pk_fma_f32 v[42:43], v[88:89], v[94:95], v[42:43] op_sel_hi:[0,1,1]
	v_pk_fma_f32 v[44:45], v[88:89], v[96:97], v[44:45] op_sel_hi:[0,1,1]
	v_pk_fma_f32 v[46:47], v[88:89], v[98:99], v[46:47] op_sel_hi:[0,1,1]
	v_pk_fma_f32 v[48:49], v[88:89], v[100:101], v[48:49] op_sel_hi:[0,1,1]
	v_pk_fma_f32 v[50:51], v[88:89], v[102:103], v[50:51] op_sel_hi:[0,1,1]
	v_pk_fma_f32 v[36:37], v[88:89], v[104:105], v[36:37] op_sel_hi:[0,1,1]
	ds_read_b128 v[90:93], v57 offset:2048
	ds_read_b128 v[94:97], v57 offset:2064
	ds_read_b128 v[98:101], v57 offset:2080
	ds_read_b128 v[102:105], v57 offset:2096
	s_waitcnt vmcnt(32) lgkmcnt(4)
	v_pk_fma_f32 v[38:39], v[88:89], v[106:107], v[38:39] op_sel:[1,0,0]
	v_pk_fma_f32 v[40:41], v[88:89], v[108:109], v[40:41] op_sel:[1,0,0]
	v_pk_fma_f32 v[42:43], v[88:89], v[110:111], v[42:43] op_sel:[1,0,0]
	v_pk_fma_f32 v[44:45], v[88:89], v[112:113], v[44:45] op_sel:[1,0,0]
	v_pk_fma_f32 v[46:47], v[88:89], v[114:115], v[46:47] op_sel:[1,0,0]
	v_pk_fma_f32 v[48:49], v[88:89], v[116:117], v[48:49] op_sel:[1,0,0]
	v_pk_fma_f32 v[50:51], v[88:89], v[118:119], v[50:51] op_sel:[1,0,0]
	v_pk_fma_f32 v[36:37], v[88:89], v[120:121], v[36:37] op_sel:[1,0,0]
	global_load_dword v58, v154, s[34:35]
	s_add_u32 s34, s34, 0x6000
	s_addc_u32 s35, s35, 0
	global_load_dword v59, v154, s[34:35]
	s_add_u32 s34, s34, 0x6000
	s_addc_u32 s35, s35, 0
	global_load_dword v60, v154, s[34:35]
	s_add_u32 s34, s34, 0x6000
	s_addc_u32 s35, s35, 0
	global_load_dword v61, v154, s[34:35]
	s_add_u32 s34, s34, 0x6000
	s_addc_u32 s35, s35, 0
	global_load_dword v62, v154, s[34:35]
	s_add_u32 s34, s34, 0x6000
	s_addc_u32 s35, s35, 0
	global_load_dword v63, v154, s[34:35]
	s_add_u32 s34, s34, 0x6000
	s_addc_u32 s35, s35, 0
	global_load_dword v64, v154, s[34:35]
	s_add_u32 s34, s34, 0x6000
	s_addc_u32 s35, s35, 0
	global_load_dword v65, v154, s[34:35]
	s_add_u32 s34, s34, 0x6000
	s_addc_u32 s35, s35, 0
	global_load_dword v66, v154, s[34:35]
	s_add_u32 s34, s34, 0x6000
	s_addc_u32 s35, s35, 0
	global_load_dword v67, v154, s[34:35]
	s_add_u32 s34, s34, 0x6000
	s_addc_u32 s35, s35, 0
	global_load_dword v68, v154, s[34:35]
	s_add_u32 s34, s34, 0x6000
	s_addc_u32 s35, s35, 0
	global_load_dword v69, v154, s[34:35]
	s_add_u32 s34, s34, 0x6000
	s_addc_u32 s35, s35, 0
	global_load_dword v70, v154, s[34:35]
	s_add_u32 s34, s34, 0x6000
	s_addc_u32 s35, s35, 0
	global_load_dword v71, v154, s[34:35]
	s_add_u32 s34, s34, 0x6000
; #define LAS __attribute__((address_space(3)))
; __device__ __forceinline__ void phase_prep(const Args& a, LAS unsigned char* lds) {
;     ...
;             for (int k = kbeg; k < kbeg + 128; ++k) { const float wv = w[(size_t)k * 6144];
;                 const LAS f32x4* s4 = (const LAS f32x4*)(sc + k * 16);
; #pragma unroll
;                 for (int q = 0; q < 4; ++q) { const f32x4 s = s4[q]; acc[4 * q] += s[0] * wv; acc[4 * q + 1] += s[1] * wv; acc[4 * q + 2] += s[2] * wv; acc[4 * q + 3] += s[3] * wv; } }
	s_addc_u32 s35, s35, 0
	global_load_dword v72, v154, s[34:35]
	s_add_u32 s34, s34, 0x6000
	s_addc_u32 s35, s35, 0
	global_load_dword v73, v154, s[34:35]
	s_add_u32 s34, s34, 0x6000
	s_addc_u32 s35, s35, 0
	global_load_dword v74, v154, s[34:35]
	s_add_u32 s34, s34, 0x6000
	s_addc_u32 s35, s35, 0
	global_load_dword v75, v154, s[34:35]
	s_add_u32 s34, s34, 0x6000
	s_addc_u32 s35, s35, 0
	global_load_dword v76, v154, s[34:35]
	s_add_u32 s34, s34, 0x6000
	s_addc_u32 s35, s35, 0
	global_load_dword v77, v154, s[34:35]
	s_add_u32 s34, s34, 0x6000
	s_addc_u32 s35, s35, 0
	global_load_dword v78, v154, s[34:35]
	s_add_u32 s34, s34, 0x6000
	s_addc_u32 s35, s35, 0
	global_load_dword v79, v154, s[34:35]
	s_add_u32 s34, s34, 0x6000
	s_addc_u32 s35, s35, 0
	global_load_dword v80, v154, s[34:35]
	s_add_u32 s34, s34, 0x6000
	s_addc_u32 s35, s35, 0
	global_load_dword v81, v154, s[34:35]
	s_add_u32 s34, s34, 0x6000
	s_addc_u32 s35, s35, 0
	global_load_dword v82, v154, s[34:35]
	s_add_u32 s34, s34, 0x6000
	s_addc_u32 s35, s35, 0
	global_load_dword v83, v154, s[34:35]
	s_add_u32 s34, s34, 0x6000
	s_addc_u32 s35, s35, 0
	global_load_dword v84, v154, s[34:35]
	s_add_u32 s34, s34, 0x6000
	s_addc_u32 s35, s35, 0
	global_load_dword v85, v154, s[34:35]
	s_add_u32 s34, s34, 0x6000
	s_addc_u32 s35, s35, 0
	global_load_dword v86, v154, s[34:35]
	s_add_u32 s34, s34, 0x6000
	s_addc_u32 s35, s35, 0
	global_load_dword v87, v154, s[34:35]
	s_add_u32 s34, s34, 0x6000
	s_addc_u32 s35, s35, 0
	global_load_dword v88, v154, s[34:35]
	s_add_u32 s34, s34, 0x6000
	s_addc_u32 s35, s35, 0
	global_load_dword v89, v154, s[34:35]
	s_add_u32 s34, s34, 0x6000
	s_addc_u32 s35, s35, 0
	ds_read_b128 v[106:109], v57 offset:2112
	ds_read_b128 v[110:113], v57 offset:2128
	ds_read_b128 v[114:117], v57 offset:2144
	ds_read_b128 v[118:121], v57 offset:2160
	s_waitcnt vmcnt(63) lgkmcnt(4)
	v_pk_fma_f32 v[38:39], v[122:123], v[90:91], v[38:39] op_sel_hi:[0,1,1]
	v_pk_fma_f32 v[40:41], v[122:123], v[92:93], v[40:41] op_sel_hi:[0,1,1]
	v_pk_fma_f32 v[42:43], v[122:123], v[94:95], v[42:43] op_sel_hi:[0,1,1]
	v_pk_fma_f32 v[44:45], v[122:123], v[96:97], v[44:45] op_sel_hi:[0,1,1]
	v_pk_fma_f32 v[46:47], v[122:123], v[98:99], v[46:47] op_sel_hi:[0,1,1]
	v_pk_fma_f32 v[48:49], v[122:123], v[100:101], v[48:49] op_sel_hi:[0,1,1]
	v_pk_fma_f32 v[50:51], v[122:123], v[102:103], v[50:51] op_sel_hi:[0,1,1]
	v_pk_fma_f32 v[36:37], v[122:123], v[104:105], v[36:37] op_sel_hi:[0,1,1]
	ds_read_b128 v[90:93], v57 offset:2176
	ds_read_b128 v[94:97], v57 offset:2192
	ds_read_b128 v[98:101], v57 offset:2208
	ds_read_b128 v[102:105], v57 offset:2224
	s_waitcnt vmcnt(62) lgkmcnt(4)
	v_pk_fma_f32 v[38:39], v[122:123], v[106:107], v[38:39] op_sel:[1,0,0]
	v_pk_fma_f32 v[40:41], v[122:123], v[108:109], v[40:41] op_sel:[1,0,0]
	v_pk_fma_f32 v[42:43], v[122:123], v[110:111], v[42:43] op_sel:[1,0,0]
	v_pk_fma_f32 v[44:45], v[122:123], v[112:113], v[44:45] op_sel:[1,0,0]
	v_pk_fma_f32 v[46:47], v[122:123], v[114:115], v[46:47] op_sel:[1,0,0]
	v_pk_fma_f32 v[48:49], v[122:123], v[116:117], v[48:49] op_sel:[1,0,0]
	v_pk_fma_f32 v[50:51], v[122:123], v[118:119], v[50:51] op_sel:[1,0,0]
	v_pk_fma_f32 v[36:37], v[122:123], v[120:121], v[36:37] op_sel:[1,0,0]
	ds_read_b128 v[106:109], v57 offset:2240
	ds_read_b128 v[110:113], v57 offset:2256
	ds_read_b128 v[114:117], v57 offset:2272
	ds_read_b128 v[118:121], v57 offset:2288
	s_waitcnt vmcnt(61) lgkmcnt(4)
	v_pk_fma_f32 v[38:39], v[124:125], v[90:91], v[38:39] op_sel_hi:[0,1,1]
	v_pk_fma_f32 v[40:41], v[124:125], v[92:93], v[40:41] op_sel_hi:[0,1,1]
	v_pk_fma_f32 v[42:43], v[124:125], v[94:95], v[42:43] op_sel_hi:[0,1,1]
	v_pk_fma_f32 v[44:45], v[124:125], v[96:97], v[44:45] op_sel_hi:[0,1,1]
	v_pk_fma_f32 v[46:47], v[124:125], v[98:99], v[46:47] op_sel_hi:[0,1,1]
	v_pk_fma_f32 v[48:49], v[124:125], v[100:101], v[48:49] op_sel_hi:[0,1,1]
	v_pk_fma_f32 v[50:51], v[124:125], v[102:103], v[50:51] op_sel_hi:[0,1,1]
	v_pk_fma_f32 v[36:37], v[124:125], v[104:105], v[36:37] op_sel_hi:[0,1,1]
	ds_read_b128 v[90:93], v57 offset:2304
	ds_read_b128 v[94:97], v57 offset:2320
	ds_read_b128 v[98:101], v57 offset:2336
	ds_read_b128 v[102:105], v57 offset:2352
	s_waitcnt vmcnt(60) lgkmcnt(4)
	v_pk_fma_f32 v[38:39], v[124:125], v[106:107], v[38:39] op_sel:[1,0,0]
	v_pk_fma_f32 v[40:41], v[124:125], v[108:109], v[40:41] op_sel:[1,0,0]
	v_pk_fma_f32 v[42:43], v[124:125], v[110:111], v[42:43] op_sel:[1,0,0]
	v_pk_fma_f32 v[44:45], v[124:125], v[112:113], v[44:45] op_sel:[1,0,0]
	v_pk_fma_f32 v[46:47], v[124:125], v[114:115], v[46:47] op_sel:[1,0,0]
	v_pk_fma_f32 v[48:49], v[124:125], v[116:117], v[48:49] op_sel:[1,0,0]
	v_pk_fma_f32 v[50:51], v[124:125], v[118:119], v[50:51] op_sel:[1,0,0]
	v_pk_fma_f32 v[36:37], v[124:125], v[120:121], v[36:37] op_sel:[1,0,0]
	ds_read_b128 v[106:109], v57 offset:2368
	ds_read_b128 v[110:113], v57 offset:2384
	ds_read_b128 v[114:117], v57 offset:2400
	ds_read_b128 v[118:121], v57 offset:2416
	s_waitcnt vmcnt(59) lgkmcnt(4)
	v_pk_fma_f32 v[38:39], v[126:127], v[90:91], v[38:39] op_sel_hi:[0,1,1]
	v_pk_fma_f32 v[40:41], v[126:127], v[92:93], v[40:41] op_sel_hi:[0,1,1]
	v_pk_fma_f32 v[42:43], v[126:127], v[94:95], v[42:43] op_sel_hi:[0,1,1]
	v_pk_fma_f32 v[44:45], v[126:127], v[96:97], v[44:45] op_sel_hi:[0,1,1]
	v_pk_fma_f32 v[46:47], v[126:127], v[98:99], v[46:47] op_sel_hi:[0,1,1]
	v_pk_fma_f32 v[48:49], v[126:127], v[100:101], v[48:49] op_sel_hi:[0,1,1]
	v_pk_fma_f32 v[50:51], v[126:127], v[102:103], v[50:51] op_sel_hi:[0,1,1]
	v_pk_fma_f32 v[36:37], v[126:127], v[104:105], v[36:37] op_sel_hi:[0,1,1]
	ds_read_b128 v[90:93], v57 offset:2432
	ds_read_b128 v[94:97], v57 offset:2448
	ds_read_b128 v[98:101], v57 offset:2464
	ds_read_b128 v[102:105], v57 offset:2480
	s_waitcnt vmcnt(58) lgkmcnt(4)
; #define LAS __attribute__((address_space(3)))
; __device__ __forceinline__ void phase_prep(const Args& a, LAS unsigned char* lds) {
;     ...
;             for (int k = kbeg; k < kbeg + 128; ++k) { const float wv = w[(size_t)k * 6144];
;                 const LAS f32x4* s4 = (const LAS f32x4*)(sc + k * 16);
; #pragma unroll
;                 for (int q = 0; q < 4; ++q) { const f32x4 s = s4[q]; acc[4 * q] += s[0] * wv; acc[4 * q + 1] += s[1] * wv; acc[4 * q + 2] += s[2] * wv; acc[4 * q + 3] += s[3] * wv; } }
	v_pk_fma_f32 v[38:39], v[126:127], v[106:107], v[38:39] op_sel:[1,0,0]
	v_pk_fma_f32 v[40:41], v[126:127], v[108:109], v[40:41] op_sel:[1,0,0]
	v_pk_fma_f32 v[42:43], v[126:127], v[110:111], v[42:43] op_sel:[1,0,0]
	v_pk_fma_f32 v[44:45], v[126:127], v[112:113], v[44:45] op_sel:[1,0,0]
	v_pk_fma_f32 v[46:47], v[126:127], v[114:115], v[46:47] op_sel:[1,0,0]
	v_pk_fma_f32 v[48:49], v[126:127], v[116:117], v[48:49] op_sel:[1,0,0]
	v_pk_fma_f32 v[50:51], v[126:127], v[118:119], v[50:51] op_sel:[1,0,0]
	v_pk_fma_f32 v[36:37], v[126:127], v[120:121], v[36:37] op_sel:[1,0,0]
	ds_read_b128 v[106:109], v57 offset:2496
	ds_read_b128 v[110:113], v57 offset:2512
	ds_read_b128 v[114:117], v57 offset:2528
	ds_read_b128 v[118:121], v57 offset:2544
	s_waitcnt vmcnt(57) lgkmcnt(4)
	v_pk_fma_f32 v[38:39], v[128:129], v[90:91], v[38:39] op_sel_hi:[0,1,1]
	v_pk_fma_f32 v[40:41], v[128:129], v[92:93], v[40:41] op_sel_hi:[0,1,1]
	v_pk_fma_f32 v[42:43], v[128:129], v[94:95], v[42:43] op_sel_hi:[0,1,1]
	v_pk_fma_f32 v[44:45], v[128:129], v[96:97], v[44:45] op_sel_hi:[0,1,1]
	v_pk_fma_f32 v[46:47], v[128:129], v[98:99], v[46:47] op_sel_hi:[0,1,1]
	v_pk_fma_f32 v[48:49], v[128:129], v[100:101], v[48:49] op_sel_hi:[0,1,1]
	v_pk_fma_f32 v[50:51], v[128:129], v[102:103], v[50:51] op_sel_hi:[0,1,1]
	v_pk_fma_f32 v[36:37], v[128:129], v[104:105], v[36:37] op_sel_hi:[0,1,1]
	ds_read_b128 v[90:93], v57 offset:2560
	ds_read_b128 v[94:97], v57 offset:2576
	ds_read_b128 v[98:101], v57 offset:2592
	ds_read_b128 v[102:105], v57 offset:2608
	s_waitcnt vmcnt(56) lgkmcnt(4)
	v_pk_fma_f32 v[38:39], v[128:129], v[106:107], v[38:39] op_sel:[1,0,0]
	v_pk_fma_f32 v[40:41], v[128:129], v[108:109], v[40:41] op_sel:[1,0,0]
	v_pk_fma_f32 v[42:43], v[128:129], v[110:111], v[42:43] op_sel:[1,0,0]
	v_pk_fma_f32 v[44:45], v[128:129], v[112:113], v[44:45] op_sel:[1,0,0]
	v_pk_fma_f32 v[46:47], v[128:129], v[114:115], v[46:47] op_sel:[1,0,0]
	v_pk_fma_f32 v[48:49], v[128:129], v[116:117], v[48:49] op_sel:[1,0,0]
	v_pk_fma_f32 v[50:51], v[128:129], v[118:119], v[50:51] op_sel:[1,0,0]
	v_pk_fma_f32 v[36:37], v[128:129], v[120:121], v[36:37] op_sel:[1,0,0]
	ds_read_b128 v[106:109], v57 offset:2624
	ds_read_b128 v[110:113], v57 offset:2640
	ds_read_b128 v[114:117], v57 offset:2656
	ds_read_b128 v[118:121], v57 offset:2672
	s_waitcnt vmcnt(55) lgkmcnt(4)
	v_pk_fma_f32 v[38:39], v[130:131], v[90:91], v[38:39] op_sel_hi:[0,1,1]
	v_pk_fma_f32 v[40:41], v[130:131], v[92:93], v[40:41] op_sel_hi:[0,1,1]
	v_pk_fma_f32 v[42:43], v[130:131], v[94:95], v[42:43] op_sel_hi:[0,1,1]
	v_pk_fma_f32 v[44:45], v[130:131], v[96:97], v[44:45] op_sel_hi:[0,1,1]
	v_pk_fma_f32 v[46:47], v[130:131], v[98:99], v[46:47] op_sel_hi:[0,1,1]
	v_pk_fma_f32 v[48:49], v[130:131], v[100:101], v[48:49] op_sel_hi:[0,1,1]
	v_pk_fma_f32 v[50:51], v[130:131], v[102:103], v[50:51] op_sel_hi:[0,1,1]
	v_pk_fma_f32 v[36:37], v[130:131], v[104:105], v[36:37] op_sel_hi:[0,1,1]
	ds_read_b128 v[90:93], v57 offset:2688
	ds_read_b128 v[94:97], v57 offset:2704
	ds_read_b128 v[98:101], v57 offset:2720
	ds_read_b128 v[102:105], v57 offset:2736
	s_waitcnt vmcnt(54) lgkmcnt(4)
	v_pk_fma_f32 v[38:39], v[130:131], v[106:107], v[38:39] op_sel:[1,0,0]
	v_pk_fma_f32 v[40:41], v[130:131], v[108:109], v[40:41] op_sel:[1,0,0]
	v_pk_fma_f32 v[42:43], v[130:131], v[110:111], v[42:43] op_sel:[1,0,0]
	v_pk_fma_f32 v[44:45], v[130:131], v[112:113], v[44:45] op_sel:[1,0,0]
	v_pk_fma_f32 v[46:47], v[130:131], v[114:115], v[46:47] op_sel:[1,0,0]
	v_pk_fma_f32 v[48:49], v[130:131], v[116:117], v[48:49] op_sel:[1,0,0]
	v_pk_fma_f32 v[50:51], v[130:131], v[118:119], v[50:51] op_sel:[1,0,0]
	v_pk_fma_f32 v[36:37], v[130:131], v[120:121], v[36:37] op_sel:[1,0,0]
	ds_read_b128 v[106:109], v57 offset:2752
	ds_read_b128 v[110:113], v57 offset:2768
	ds_read_b128 v[114:117], v57 offset:2784
	ds_read_b128 v[118:121], v57 offset:2800
	s_waitcnt vmcnt(53) lgkmcnt(4)
	v_pk_fma_f32 v[38:39], v[132:133], v[90:91], v[38:39] op_sel_hi:[0,1,1]
	v_pk_fma_f32 v[40:41], v[132:133], v[92:93], v[40:41] op_sel_hi:[0,1,1]
	v_pk_fma_f32 v[42:43], v[132:133], v[94:95], v[42:43] op_sel_hi:[0,1,1]
	v_pk_fma_f32 v[44:45], v[132:133], v[96:97], v[44:45] op_sel_hi:[0,1,1]
	v_pk_fma_f32 v[46:47], v[132:133], v[98:99], v[46:47] op_sel_hi:[0,1,1]
	v_pk_fma_f32 v[48:49], v[132:133], v[100:101], v[48:49] op_sel_hi:[0,1,1]
	v_pk_fma_f32 v[50:51], v[132:133], v[102:103], v[50:51] op_sel_hi:[0,1,1]
	v_pk_fma_f32 v[36:37], v[132:133], v[104:105], v[36:37] op_sel_hi:[0,1,1]
	ds_read_b128 v[90:93], v57 offset:2816
	ds_read_b128 v[94:97], v57 offset:2832
	ds_read_b128 v[98:101], v57 offset:2848
	ds_read_b128 v[102:105], v57 offset:2864
	s_waitcnt vmcnt(52) lgkmcnt(4)
	v_pk_fma_f32 v[38:39], v[132:133], v[106:107], v[38:39] op_sel:[1,0,0]
	v_pk_fma_f32 v[40:41], v[132:133], v[108:109], v[40:41] op_sel:[1,0,0]
	v_pk_fma_f32 v[42:43], v[132:133], v[110:111], v[42:43] op_sel:[1,0,0]
	v_pk_fma_f32 v[44:45], v[132:133], v[112:113], v[44:45] op_sel:[1,0,0]
	v_pk_fma_f32 v[46:47], v[132:133], v[114:115], v[46:47] op_sel:[1,0,0]
	v_pk_fma_f32 v[48:49], v[132:133], v[116:117], v[48:49] op_sel:[1,0,0]
	v_pk_fma_f32 v[50:51], v[132:133], v[118:119], v[50:51] op_sel:[1,0,0]
	v_pk_fma_f32 v[36:37], v[132:133], v[120:121], v[36:37] op_sel:[1,0,0]
	ds_read_b128 v[106:109], v57 offset:2880
	ds_read_b128 v[110:113], v57 offset:2896
	ds_read_b128 v[114:117], v57 offset:2912
	ds_read_b128 v[118:121], v57 offset:2928
	s_waitcnt vmcnt(51) lgkmcnt(4)
; #define LAS __attribute__((address_space(3)))
; __device__ __forceinline__ void phase_prep(const Args& a, LAS unsigned char* lds) {
;     ...
;             for (int k = kbeg; k < kbeg + 128; ++k) { const float wv = w[(size_t)k * 6144];
;                 const LAS f32x4* s4 = (const LAS f32x4*)(sc + k * 16);
; #pragma unroll
;                 for (int q = 0; q < 4; ++q) { const f32x4 s = s4[q]; acc[4 * q] += s[0] * wv; acc[4 * q + 1] += s[1] * wv; acc[4 * q + 2] += s[2] * wv; acc[4 * q + 3] += s[3] * wv; } }
	v_pk_fma_f32 v[38:39], v[134:135], v[90:91], v[38:39] op_sel_hi:[0,1,1]
	v_pk_fma_f32 v[40:41], v[134:135], v[92:93], v[40:41] op_sel_hi:[0,1,1]
	v_pk_fma_f32 v[42:43], v[134:135], v[94:95], v[42:43] op_sel_hi:[0,1,1]
	v_pk_fma_f32 v[44:45], v[134:135], v[96:97], v[44:45] op_sel_hi:[0,1,1]
	v_pk_fma_f32 v[46:47], v[134:135], v[98:99], v[46:47] op_sel_hi:[0,1,1]
	v_pk_fma_f32 v[48:49], v[134:135], v[100:101], v[48:49] op_sel_hi:[0,1,1]
	v_pk_fma_f32 v[50:51], v[134:135], v[102:103], v[50:51] op_sel_hi:[0,1,1]
	v_pk_fma_f32 v[36:37], v[134:135], v[104:105], v[36:37] op_sel_hi:[0,1,1]
	ds_read_b128 v[90:93], v57 offset:2944
	ds_read_b128 v[94:97], v57 offset:2960
	ds_read_b128 v[98:101], v57 offset:2976
	ds_read_b128 v[102:105], v57 offset:2992
	s_waitcnt vmcnt(50) lgkmcnt(4)
	v_pk_fma_f32 v[38:39], v[134:135], v[106:107], v[38:39] op_sel:[1,0,0]
	v_pk_fma_f32 v[40:41], v[134:135], v[108:109], v[40:41] op_sel:[1,0,0]
	v_pk_fma_f32 v[42:43], v[134:135], v[110:111], v[42:43] op_sel:[1,0,0]
	v_pk_fma_f32 v[44:45], v[134:135], v[112:113], v[44:45] op_sel:[1,0,0]
	v_pk_fma_f32 v[46:47], v[134:135], v[114:115], v[46:47] op_sel:[1,0,0]
	v_pk_fma_f32 v[48:49], v[134:135], v[116:117], v[48:49] op_sel:[1,0,0]
	v_pk_fma_f32 v[50:51], v[134:135], v[118:119], v[50:51] op_sel:[1,0,0]
	v_pk_fma_f32 v[36:37], v[134:135], v[120:121], v[36:37] op_sel:[1,0,0]
	ds_read_b128 v[106:109], v57 offset:3008
	ds_read_b128 v[110:113], v57 offset:3024
	ds_read_b128 v[114:117], v57 offset:3040
	ds_read_b128 v[118:121], v57 offset:3056
	s_waitcnt vmcnt(49) lgkmcnt(4)
	v_pk_fma_f32 v[38:39], v[136:137], v[90:91], v[38:39] op_sel_hi:[0,1,1]
	v_pk_fma_f32 v[40:41], v[136:137], v[92:93], v[40:41] op_sel_hi:[0,1,1]
	v_pk_fma_f32 v[42:43], v[136:137], v[94:95], v[42:43] op_sel_hi:[0,1,1]
	v_pk_fma_f32 v[44:45], v[136:137], v[96:97], v[44:45] op_sel_hi:[0,1,1]
	v_pk_fma_f32 v[46:47], v[136:137], v[98:99], v[46:47] op_sel_hi:[0,1,1]
	v_pk_fma_f32 v[48:49], v[136:137], v[100:101], v[48:49] op_sel_hi:[0,1,1]
	v_pk_fma_f32 v[50:51], v[136:137], v[102:103], v[50:51] op_sel_hi:[0,1,1]
	v_pk_fma_f32 v[36:37], v[136:137], v[104:105], v[36:37] op_sel_hi:[0,1,1]
	ds_read_b128 v[90:93], v57 offset:3072
	ds_read_b128 v[94:97], v57 offset:3088
	ds_read_b128 v[98:101], v57 offset:3104
	ds_read_b128 v[102:105], v57 offset:3120
	s_waitcnt vmcnt(48) lgkmcnt(4)
	v_pk_fma_f32 v[38:39], v[136:137], v[106:107], v[38:39] op_sel:[1,0,0]
	v_pk_fma_f32 v[40:41], v[136:137], v[108:109], v[40:41] op_sel:[1,0,0]
	v_pk_fma_f32 v[42:43], v[136:137], v[110:111], v[42:43] op_sel:[1,0,0]
	v_pk_fma_f32 v[44:45], v[136:137], v[112:113], v[44:45] op_sel:[1,0,0]
	v_pk_fma_f32 v[46:47], v[136:137], v[114:115], v[46:47] op_sel:[1,0,0]
	v_pk_fma_f32 v[48:49], v[136:137], v[116:117], v[48:49] op_sel:[1,0,0]
	v_pk_fma_f32 v[50:51], v[136:137], v[118:119], v[50:51] op_sel:[1,0,0]
	v_pk_fma_f32 v[36:37], v[136:137], v[120:121], v[36:37] op_sel:[1,0,0]
	ds_read_b128 v[106:109], v57 offset:3136
	ds_read_b128 v[110:113], v57 offset:3152
	ds_read_b128 v[114:117], v57 offset:3168
	ds_read_b128 v[118:121], v57 offset:3184
	s_waitcnt vmcnt(47) lgkmcnt(4)
	v_pk_fma_f32 v[38:39], v[138:139], v[90:91], v[38:39] op_sel_hi:[0,1,1]
	v_pk_fma_f32 v[40:41], v[138:139], v[92:93], v[40:41] op_sel_hi:[0,1,1]
	v_pk_fma_f32 v[42:43], v[138:139], v[94:95], v[42:43] op_sel_hi:[0,1,1]
	v_pk_fma_f32 v[44:45], v[138:139], v[96:97], v[44:45] op_sel_hi:[0,1,1]
	v_pk_fma_f32 v[46:47], v[138:139], v[98:99], v[46:47] op_sel_hi:[0,1,1]
	v_pk_fma_f32 v[48:49], v[138:139], v[100:101], v[48:49] op_sel_hi:[0,1,1]
	v_pk_fma_f32 v[50:51], v[138:139], v[102:103], v[50:51] op_sel_hi:[0,1,1]
	v_pk_fma_f32 v[36:37], v[138:139], v[104:105], v[36:37] op_sel_hi:[0,1,1]
	ds_read_b128 v[90:93], v57 offset:3200
	ds_read_b128 v[94:97], v57 offset:3216
	ds_read_b128 v[98:101], v57 offset:3232
	ds_read_b128 v[102:105], v57 offset:3248
	s_waitcnt vmcnt(46) lgkmcnt(4)
	v_pk_fma_f32 v[38:39], v[138:139], v[106:107], v[38:39] op_sel:[1,0,0]
	v_pk_fma_f32 v[40:41], v[138:139], v[108:109], v[40:41] op_sel:[1,0,0]
	v_pk_fma_f32 v[42:43], v[138:139], v[110:111], v[42:43] op_sel:[1,0,0]
	v_pk_fma_f32 v[44:45], v[138:139], v[112:113], v[44:45] op_sel:[1,0,0]
	v_pk_fma_f32 v[46:47], v[138:139], v[114:115], v[46:47] op_sel:[1,0,0]
	v_pk_fma_f32 v[48:49], v[138:139], v[116:117], v[48:49] op_sel:[1,0,0]
	v_pk_fma_f32 v[50:51], v[138:139], v[118:119], v[50:51] op_sel:[1,0,0]
	v_pk_fma_f32 v[36:37], v[138:139], v[120:121], v[36:37] op_sel:[1,0,0]
	ds_read_b128 v[106:109], v57 offset:3264
	ds_read_b128 v[110:113], v57 offset:3280
	ds_read_b128 v[114:117], v57 offset:3296
	ds_read_b128 v[118:121], v57 offset:3312
	s_waitcnt vmcnt(45) lgkmcnt(4)
	v_pk_fma_f32 v[38:39], v[140:141], v[90:91], v[38:39] op_sel_hi:[0,1,1]
	v_pk_fma_f32 v[40:41], v[140:141], v[92:93], v[40:41] op_sel_hi:[0,1,1]
	v_pk_fma_f32 v[42:43], v[140:141], v[94:95], v[42:43] op_sel_hi:[0,1,1]
	v_pk_fma_f32 v[44:45], v[140:141], v[96:97], v[44:45] op_sel_hi:[0,1,1]
	v_pk_fma_f32 v[46:47], v[140:141], v[98:99], v[46:47] op_sel_hi:[0,1,1]
	v_pk_fma_f32 v[48:49], v[140:141], v[100:101], v[48:49] op_sel_hi:[0,1,1]
	v_pk_fma_f32 v[50:51], v[140:141], v[102:103], v[50:51] op_sel_hi:[0,1,1]
	v_pk_fma_f32 v[36:37], v[140:141], v[104:105], v[36:37] op_sel_hi:[0,1,1]
	ds_read_b128 v[90:93], v57 offset:3328
	ds_read_b128 v[94:97], v57 offset:3344
	ds_read_b128 v[98:101], v57 offset:3360
	ds_read_b128 v[102:105], v57 offset:3376
	s_waitcnt vmcnt(44) lgkmcnt(4)
; #define LAS __attribute__((address_space(3)))
; __device__ __forceinline__ void phase_prep(const Args& a, LAS unsigned char* lds) {
;     ...
;             for (int k = kbeg; k < kbeg + 128; ++k) { const float wv = w[(size_t)k * 6144];
;                 const LAS f32x4* s4 = (const LAS f32x4*)(sc + k * 16);
; #pragma unroll
;                 for (int q = 0; q < 4; ++q) { const f32x4 s = s4[q]; acc[4 * q] += s[0] * wv; acc[4 * q + 1] += s[1] * wv; acc[4 * q + 2] += s[2] * wv; acc[4 * q + 3] += s[3] * wv; } }
	v_pk_fma_f32 v[38:39], v[140:141], v[106:107], v[38:39] op_sel:[1,0,0]
	v_pk_fma_f32 v[40:41], v[140:141], v[108:109], v[40:41] op_sel:[1,0,0]
	v_pk_fma_f32 v[42:43], v[140:141], v[110:111], v[42:43] op_sel:[1,0,0]
	v_pk_fma_f32 v[44:45], v[140:141], v[112:113], v[44:45] op_sel:[1,0,0]
	v_pk_fma_f32 v[46:47], v[140:141], v[114:115], v[46:47] op_sel:[1,0,0]
	v_pk_fma_f32 v[48:49], v[140:141], v[116:117], v[48:49] op_sel:[1,0,0]
	v_pk_fma_f32 v[50:51], v[140:141], v[118:119], v[50:51] op_sel:[1,0,0]
	v_pk_fma_f32 v[36:37], v[140:141], v[120:121], v[36:37] op_sel:[1,0,0]
	ds_read_b128 v[106:109], v57 offset:3392
	ds_read_b128 v[110:113], v57 offset:3408
	ds_read_b128 v[114:117], v57 offset:3424
	ds_read_b128 v[118:121], v57 offset:3440
	s_waitcnt vmcnt(43) lgkmcnt(4)
	v_pk_fma_f32 v[38:39], v[142:143], v[90:91], v[38:39] op_sel_hi:[0,1,1]
	v_pk_fma_f32 v[40:41], v[142:143], v[92:93], v[40:41] op_sel_hi:[0,1,1]
	v_pk_fma_f32 v[42:43], v[142:143], v[94:95], v[42:43] op_sel_hi:[0,1,1]
	v_pk_fma_f32 v[44:45], v[142:143], v[96:97], v[44:45] op_sel_hi:[0,1,1]
	v_pk_fma_f32 v[46:47], v[142:143], v[98:99], v[46:47] op_sel_hi:[0,1,1]
	v_pk_fma_f32 v[48:49], v[142:143], v[100:101], v[48:49] op_sel_hi:[0,1,1]
	v_pk_fma_f32 v[50:51], v[142:143], v[102:103], v[50:51] op_sel_hi:[0,1,1]
	v_pk_fma_f32 v[36:37], v[142:143], v[104:105], v[36:37] op_sel_hi:[0,1,1]
	ds_read_b128 v[90:93], v57 offset:3456
	ds_read_b128 v[94:97], v57 offset:3472
	ds_read_b128 v[98:101], v57 offset:3488
	ds_read_b128 v[102:105], v57 offset:3504
	s_waitcnt vmcnt(42) lgkmcnt(4)
	v_pk_fma_f32 v[38:39], v[142:143], v[106:107], v[38:39] op_sel:[1,0,0]
	v_pk_fma_f32 v[40:41], v[142:143], v[108:109], v[40:41] op_sel:[1,0,0]
	v_pk_fma_f32 v[42:43], v[142:143], v[110:111], v[42:43] op_sel:[1,0,0]
	v_pk_fma_f32 v[44:45], v[142:143], v[112:113], v[44:45] op_sel:[1,0,0]
	v_pk_fma_f32 v[46:47], v[142:143], v[114:115], v[46:47] op_sel:[1,0,0]
	v_pk_fma_f32 v[48:49], v[142:143], v[116:117], v[48:49] op_sel:[1,0,0]
	v_pk_fma_f32 v[50:51], v[142:143], v[118:119], v[50:51] op_sel:[1,0,0]
	v_pk_fma_f32 v[36:37], v[142:143], v[120:121], v[36:37] op_sel:[1,0,0]
	ds_read_b128 v[106:109], v57 offset:3520
	ds_read_b128 v[110:113], v57 offset:3536
	ds_read_b128 v[114:117], v57 offset:3552
	ds_read_b128 v[118:121], v57 offset:3568
	s_waitcnt vmcnt(41) lgkmcnt(4)
	v_pk_fma_f32 v[38:39], v[144:145], v[90:91], v[38:39] op_sel_hi:[0,1,1]
	v_pk_fma_f32 v[40:41], v[144:145], v[92:93], v[40:41] op_sel_hi:[0,1,1]
	v_pk_fma_f32 v[42:43], v[144:145], v[94:95], v[42:43] op_sel_hi:[0,1,1]
	v_pk_fma_f32 v[44:45], v[144:145], v[96:97], v[44:45] op_sel_hi:[0,1,1]
	v_pk_fma_f32 v[46:47], v[144:145], v[98:99], v[46:47] op_sel_hi:[0,1,1]
	v_pk_fma_f32 v[48:49], v[144:145], v[100:101], v[48:49] op_sel_hi:[0,1,1]
	v_pk_fma_f32 v[50:51], v[144:145], v[102:103], v[50:51] op_sel_hi:[0,1,1]
	v_pk_fma_f32 v[36:37], v[144:145], v[104:105], v[36:37] op_sel_hi:[0,1,1]
	ds_read_b128 v[90:93], v57 offset:3584
	ds_read_b128 v[94:97], v57 offset:3600
	ds_read_b128 v[98:101], v57 offset:3616
	ds_read_b128 v[102:105], v57 offset:3632
	s_waitcnt vmcnt(40) lgkmcnt(4)
	v_pk_fma_f32 v[38:39], v[144:145], v[106:107], v[38:39] op_sel:[1,0,0]
	v_pk_fma_f32 v[40:41], v[144:145], v[108:109], v[40:41] op_sel:[1,0,0]
	v_pk_fma_f32 v[42:43], v[144:145], v[110:111], v[42:43] op_sel:[1,0,0]
	v_pk_fma_f32 v[44:45], v[144:145], v[112:113], v[44:45] op_sel:[1,0,0]
	v_pk_fma_f32 v[46:47], v[144:145], v[114:115], v[46:47] op_sel:[1,0,0]
	v_pk_fma_f32 v[48:49], v[144:145], v[116:117], v[48:49] op_sel:[1,0,0]
	v_pk_fma_f32 v[50:51], v[144:145], v[118:119], v[50:51] op_sel:[1,0,0]
	v_pk_fma_f32 v[36:37], v[144:145], v[120:121], v[36:37] op_sel:[1,0,0]
	ds_read_b128 v[106:109], v57 offset:3648
	ds_read_b128 v[110:113], v57 offset:3664
	ds_read_b128 v[114:117], v57 offset:3680
	ds_read_b128 v[118:121], v57 offset:3696
	s_waitcnt vmcnt(39) lgkmcnt(4)
	v_pk_fma_f32 v[38:39], v[146:147], v[90:91], v[38:39] op_sel_hi:[0,1,1]
	v_pk_fma_f32 v[40:41], v[146:147], v[92:93], v[40:41] op_sel_hi:[0,1,1]
	v_pk_fma_f32 v[42:43], v[146:147], v[94:95], v[42:43] op_sel_hi:[0,1,1]
	v_pk_fma_f32 v[44:45], v[146:147], v[96:97], v[44:45] op_sel_hi:[0,1,1]
	v_pk_fma_f32 v[46:47], v[146:147], v[98:99], v[46:47] op_sel_hi:[0,1,1]
	v_pk_fma_f32 v[48:49], v[146:147], v[100:101], v[48:49] op_sel_hi:[0,1,1]
	v_pk_fma_f32 v[50:51], v[146:147], v[102:103], v[50:51] op_sel_hi:[0,1,1]
	v_pk_fma_f32 v[36:37], v[146:147], v[104:105], v[36:37] op_sel_hi:[0,1,1]
	ds_read_b128 v[90:93], v57 offset:3712
	ds_read_b128 v[94:97], v57 offset:3728
	ds_read_b128 v[98:101], v57 offset:3744
	ds_read_b128 v[102:105], v57 offset:3760
	s_waitcnt vmcnt(38) lgkmcnt(4)
	v_pk_fma_f32 v[38:39], v[146:147], v[106:107], v[38:39] op_sel:[1,0,0]
	v_pk_fma_f32 v[40:41], v[146:147], v[108:109], v[40:41] op_sel:[1,0,0]
	v_pk_fma_f32 v[42:43], v[146:147], v[110:111], v[42:43] op_sel:[1,0,0]
	v_pk_fma_f32 v[44:45], v[146:147], v[112:113], v[44:45] op_sel:[1,0,0]
	v_pk_fma_f32 v[46:47], v[146:147], v[114:115], v[46:47] op_sel:[1,0,0]
	v_pk_fma_f32 v[48:49], v[146:147], v[116:117], v[48:49] op_sel:[1,0,0]
	v_pk_fma_f32 v[50:51], v[146:147], v[118:119], v[50:51] op_sel:[1,0,0]
	v_pk_fma_f32 v[36:37], v[146:147], v[120:121], v[36:37] op_sel:[1,0,0]
	ds_read_b128 v[106:109], v57 offset:3776
	ds_read_b128 v[110:113], v57 offset:3792
	ds_read_b128 v[114:117], v57 offset:3808
	ds_read_b128 v[118:121], v57 offset:3824
	s_waitcnt vmcnt(37) lgkmcnt(4)
; #define LAS __attribute__((address_space(3)))
; __device__ __forceinline__ void phase_prep(const Args& a, LAS unsigned char* lds) {
;     ...
;             for (int k = kbeg; k < kbeg + 128; ++k) { const float wv = w[(size_t)k * 6144];
;                 const LAS f32x4* s4 = (const LAS f32x4*)(sc + k * 16);
; #pragma unroll
;                 for (int q = 0; q < 4; ++q) { const f32x4 s = s4[q]; acc[4 * q] += s[0] * wv; acc[4 * q + 1] += s[1] * wv; acc[4 * q + 2] += s[2] * wv; acc[4 * q + 3] += s[3] * wv; } }
	v_pk_fma_f32 v[38:39], v[148:149], v[90:91], v[38:39] op_sel_hi:[0,1,1]
	v_pk_fma_f32 v[40:41], v[148:149], v[92:93], v[40:41] op_sel_hi:[0,1,1]
	v_pk_fma_f32 v[42:43], v[148:149], v[94:95], v[42:43] op_sel_hi:[0,1,1]
	v_pk_fma_f32 v[44:45], v[148:149], v[96:97], v[44:45] op_sel_hi:[0,1,1]
	v_pk_fma_f32 v[46:47], v[148:149], v[98:99], v[46:47] op_sel_hi:[0,1,1]
	v_pk_fma_f32 v[48:49], v[148:149], v[100:101], v[48:49] op_sel_hi:[0,1,1]
	v_pk_fma_f32 v[50:51], v[148:149], v[102:103], v[50:51] op_sel_hi:[0,1,1]
	v_pk_fma_f32 v[36:37], v[148:149], v[104:105], v[36:37] op_sel_hi:[0,1,1]
	ds_read_b128 v[90:93], v57 offset:3840
	ds_read_b128 v[94:97], v57 offset:3856
	ds_read_b128 v[98:101], v57 offset:3872
	ds_read_b128 v[102:105], v57 offset:3888
	s_waitcnt vmcnt(36) lgkmcnt(4)
	v_pk_fma_f32 v[38:39], v[148:149], v[106:107], v[38:39] op_sel:[1,0,0]
	v_pk_fma_f32 v[40:41], v[148:149], v[108:109], v[40:41] op_sel:[1,0,0]
	v_pk_fma_f32 v[42:43], v[148:149], v[110:111], v[42:43] op_sel:[1,0,0]
	v_pk_fma_f32 v[44:45], v[148:149], v[112:113], v[44:45] op_sel:[1,0,0]
	v_pk_fma_f32 v[46:47], v[148:149], v[114:115], v[46:47] op_sel:[1,0,0]
	v_pk_fma_f32 v[48:49], v[148:149], v[116:117], v[48:49] op_sel:[1,0,0]
	v_pk_fma_f32 v[50:51], v[148:149], v[118:119], v[50:51] op_sel:[1,0,0]
	v_pk_fma_f32 v[36:37], v[148:149], v[120:121], v[36:37] op_sel:[1,0,0]
	ds_read_b128 v[106:109], v57 offset:3904
	ds_read_b128 v[110:113], v57 offset:3920
	ds_read_b128 v[114:117], v57 offset:3936
	ds_read_b128 v[118:121], v57 offset:3952
	s_waitcnt vmcnt(35) lgkmcnt(4)
	v_pk_fma_f32 v[38:39], v[150:151], v[90:91], v[38:39] op_sel_hi:[0,1,1]
	v_pk_fma_f32 v[40:41], v[150:151], v[92:93], v[40:41] op_sel_hi:[0,1,1]
	v_pk_fma_f32 v[42:43], v[150:151], v[94:95], v[42:43] op_sel_hi:[0,1,1]
	v_pk_fma_f32 v[44:45], v[150:151], v[96:97], v[44:45] op_sel_hi:[0,1,1]
	v_pk_fma_f32 v[46:47], v[150:151], v[98:99], v[46:47] op_sel_hi:[0,1,1]
	v_pk_fma_f32 v[48:49], v[150:151], v[100:101], v[48:49] op_sel_hi:[0,1,1]
	v_pk_fma_f32 v[50:51], v[150:151], v[102:103], v[50:51] op_sel_hi:[0,1,1]
	v_pk_fma_f32 v[36:37], v[150:151], v[104:105], v[36:37] op_sel_hi:[0,1,1]
	ds_read_b128 v[90:93], v57 offset:3968
	ds_read_b128 v[94:97], v57 offset:3984
	ds_read_b128 v[98:101], v57 offset:4000
	ds_read_b128 v[102:105], v57 offset:4016
	s_waitcnt vmcnt(34) lgkmcnt(4)
	v_pk_fma_f32 v[38:39], v[150:151], v[106:107], v[38:39] op_sel:[1,0,0]
	v_pk_fma_f32 v[40:41], v[150:151], v[108:109], v[40:41] op_sel:[1,0,0]
	v_pk_fma_f32 v[42:43], v[150:151], v[110:111], v[42:43] op_sel:[1,0,0]
	v_pk_fma_f32 v[44:45], v[150:151], v[112:113], v[44:45] op_sel:[1,0,0]
	v_pk_fma_f32 v[46:47], v[150:151], v[114:115], v[46:47] op_sel:[1,0,0]
	v_pk_fma_f32 v[48:49], v[150:151], v[116:117], v[48:49] op_sel:[1,0,0]
	v_pk_fma_f32 v[50:51], v[150:151], v[118:119], v[50:51] op_sel:[1,0,0]
	v_pk_fma_f32 v[36:37], v[150:151], v[120:121], v[36:37] op_sel:[1,0,0]
	ds_read_b128 v[106:109], v57 offset:4032
	ds_read_b128 v[110:113], v57 offset:4048
	ds_read_b128 v[114:117], v57 offset:4064
	ds_read_b128 v[118:121], v57 offset:4080
	s_waitcnt vmcnt(33) lgkmcnt(4)
	v_pk_fma_f32 v[38:39], v[152:153], v[90:91], v[38:39] op_sel_hi:[0,1,1]
	v_pk_fma_f32 v[40:41], v[152:153], v[92:93], v[40:41] op_sel_hi:[0,1,1]
	v_pk_fma_f32 v[42:43], v[152:153], v[94:95], v[42:43] op_sel_hi:[0,1,1]
	v_pk_fma_f32 v[44:45], v[152:153], v[96:97], v[44:45] op_sel_hi:[0,1,1]
	v_pk_fma_f32 v[46:47], v[152:153], v[98:99], v[46:47] op_sel_hi:[0,1,1]
	v_pk_fma_f32 v[48:49], v[152:153], v[100:101], v[48:49] op_sel_hi:[0,1,1]
	v_pk_fma_f32 v[50:51], v[152:153], v[102:103], v[50:51] op_sel_hi:[0,1,1]
	v_pk_fma_f32 v[36:37], v[152:153], v[104:105], v[36:37] op_sel_hi:[0,1,1]
	ds_read_b128 v[90:93], v57 offset:4096
	ds_read_b128 v[94:97], v57 offset:4112
	ds_read_b128 v[98:101], v57 offset:4128
	ds_read_b128 v[102:105], v57 offset:4144
	s_waitcnt vmcnt(32) lgkmcnt(4)
	v_pk_fma_f32 v[38:39], v[152:153], v[106:107], v[38:39] op_sel:[1,0,0]
	v_pk_fma_f32 v[40:41], v[152:153], v[108:109], v[40:41] op_sel:[1,0,0]
	v_pk_fma_f32 v[42:43], v[152:153], v[110:111], v[42:43] op_sel:[1,0,0]
	v_pk_fma_f32 v[44:45], v[152:153], v[112:113], v[44:45] op_sel:[1,0,0]
	v_pk_fma_f32 v[46:47], v[152:153], v[114:115], v[46:47] op_sel:[1,0,0]
	v_pk_fma_f32 v[48:49], v[152:153], v[116:117], v[48:49] op_sel:[1,0,0]
	v_pk_fma_f32 v[50:51], v[152:153], v[118:119], v[50:51] op_sel:[1,0,0]
	v_pk_fma_f32 v[36:37], v[152:153], v[120:121], v[36:37] op_sel:[1,0,0]
	global_load_dword v122, v154, s[34:35]
	s_add_u32 s34, s34, 0x6000
	s_addc_u32 s35, s35, 0
	global_load_dword v123, v154, s[34:35]
	s_add_u32 s34, s34, 0x6000
	s_addc_u32 s35, s35, 0
	global_load_dword v124, v154, s[34:35]
	s_add_u32 s34, s34, 0x6000
	s_addc_u32 s35, s35, 0
	global_load_dword v125, v154, s[34:35]
	s_add_u32 s34, s34, 0x6000
	s_addc_u32 s35, s35, 0
	global_load_dword v126, v154, s[34:35]
	s_add_u32 s34, s34, 0x6000
	s_addc_u32 s35, s35, 0
	global_load_dword v127, v154, s[34:35]
	s_add_u32 s34, s34, 0x6000
	s_addc_u32 s35, s35, 0
	global_load_dword v128, v154, s[34:35]
	s_add_u32 s34, s34, 0x6000
	s_addc_u32 s35, s35, 0
	global_load_dword v129, v154, s[34:35]
	s_add_u32 s34, s34, 0x6000
	s_addc_u32 s35, s35, 0
	global_load_dword v130, v154, s[34:35]
	s_add_u32 s34, s34, 0x6000
	s_addc_u32 s35, s35, 0
	global_load_dword v131, v154, s[34:35]
	s_add_u32 s34, s34, 0x6000
	s_addc_u32 s35, s35, 0
	global_load_dword v132, v154, s[34:35]
	s_add_u32 s34, s34, 0x6000
	s_addc_u32 s35, s35, 0
	global_load_dword v133, v154, s[34:35]
	s_add_u32 s34, s34, 0x6000
	s_addc_u32 s35, s35, 0
	global_load_dword v134, v154, s[34:35]
; #define LAS __attribute__((address_space(3)))
; __device__ __forceinline__ void phase_prep(const Args& a, LAS unsigned char* lds) {
;     ...
;             for (int k = kbeg; k < kbeg + 128; ++k) { const float wv = w[(size_t)k * 6144];
;                 const LAS f32x4* s4 = (const LAS f32x4*)(sc + k * 16);
; #pragma unroll
;                 for (int q = 0; q < 4; ++q) { const f32x4 s = s4[q]; acc[4 * q] += s[0] * wv; acc[4 * q + 1] += s[1] * wv; acc[4 * q + 2] += s[2] * wv; acc[4 * q + 3] += s[3] * wv; } }
	s_add_u32 s34, s34, 0x6000
	s_addc_u32 s35, s35, 0
	global_load_dword v135, v154, s[34:35]
	s_add_u32 s34, s34, 0x6000
	s_addc_u32 s35, s35, 0
	global_load_dword v136, v154, s[34:35]
	s_add_u32 s34, s34, 0x6000
	s_addc_u32 s35, s35, 0
	global_load_dword v137, v154, s[34:35]
	s_add_u32 s34, s34, 0x6000
	s_addc_u32 s35, s35, 0
	global_load_dword v138, v154, s[34:35]
	s_add_u32 s34, s34, 0x6000
	s_addc_u32 s35, s35, 0
	global_load_dword v139, v154, s[34:35]
	s_add_u32 s34, s34, 0x6000
	s_addc_u32 s35, s35, 0
	global_load_dword v140, v154, s[34:35]
	s_add_u32 s34, s34, 0x6000
	s_addc_u32 s35, s35, 0
	global_load_dword v141, v154, s[34:35]
	s_add_u32 s34, s34, 0x6000
	s_addc_u32 s35, s35, 0
	global_load_dword v142, v154, s[34:35]
	s_add_u32 s34, s34, 0x6000
	s_addc_u32 s35, s35, 0
	global_load_dword v143, v154, s[34:35]
	s_add_u32 s34, s34, 0x6000
	s_addc_u32 s35, s35, 0
	global_load_dword v144, v154, s[34:35]
	s_add_u32 s34, s34, 0x6000
	s_addc_u32 s35, s35, 0
	global_load_dword v145, v154, s[34:35]
	s_add_u32 s34, s34, 0x6000
	s_addc_u32 s35, s35, 0
	global_load_dword v146, v154, s[34:35]
	s_add_u32 s34, s34, 0x6000
	s_addc_u32 s35, s35, 0
	global_load_dword v147, v154, s[34:35]
	s_add_u32 s34, s34, 0x6000
	s_addc_u32 s35, s35, 0
	global_load_dword v148, v154, s[34:35]
	s_add_u32 s34, s34, 0x6000
	s_addc_u32 s35, s35, 0
	global_load_dword v149, v154, s[34:35]
	s_add_u32 s34, s34, 0x6000
	s_addc_u32 s35, s35, 0
	global_load_dword v150, v154, s[34:35]
	s_add_u32 s34, s34, 0x6000
	s_addc_u32 s35, s35, 0
	global_load_dword v151, v154, s[34:35]
	s_add_u32 s34, s34, 0x6000
	s_addc_u32 s35, s35, 0
	global_load_dword v152, v154, s[34:35]
	s_add_u32 s34, s34, 0x6000
	s_addc_u32 s35, s35, 0
	global_load_dword v153, v154, s[34:35]
	s_add_u32 s34, s34, 0x6000
	s_addc_u32 s35, s35, 0
	ds_read_b128 v[106:109], v57 offset:4160
	ds_read_b128 v[110:113], v57 offset:4176
	ds_read_b128 v[114:117], v57 offset:4192
	ds_read_b128 v[118:121], v57 offset:4208
	s_waitcnt vmcnt(63) lgkmcnt(4)
	v_pk_fma_f32 v[38:39], v[58:59], v[90:91], v[38:39] op_sel_hi:[0,1,1]
	v_pk_fma_f32 v[40:41], v[58:59], v[92:93], v[40:41] op_sel_hi:[0,1,1]
	v_pk_fma_f32 v[42:43], v[58:59], v[94:95], v[42:43] op_sel_hi:[0,1,1]
	v_pk_fma_f32 v[44:45], v[58:59], v[96:97], v[44:45] op_sel_hi:[0,1,1]
	v_pk_fma_f32 v[46:47], v[58:59], v[98:99], v[46:47] op_sel_hi:[0,1,1]
	v_pk_fma_f32 v[48:49], v[58:59], v[100:101], v[48:49] op_sel_hi:[0,1,1]
	v_pk_fma_f32 v[50:51], v[58:59], v[102:103], v[50:51] op_sel_hi:[0,1,1]
	v_pk_fma_f32 v[36:37], v[58:59], v[104:105], v[36:37] op_sel_hi:[0,1,1]
	ds_read_b128 v[90:93], v57 offset:4224
	ds_read_b128 v[94:97], v57 offset:4240
	ds_read_b128 v[98:101], v57 offset:4256
	ds_read_b128 v[102:105], v57 offset:4272
	s_waitcnt vmcnt(62) lgkmcnt(4)
	v_pk_fma_f32 v[38:39], v[58:59], v[106:107], v[38:39] op_sel:[1,0,0]
	v_pk_fma_f32 v[40:41], v[58:59], v[108:109], v[40:41] op_sel:[1,0,0]
	v_pk_fma_f32 v[42:43], v[58:59], v[110:111], v[42:43] op_sel:[1,0,0]
	v_pk_fma_f32 v[44:45], v[58:59], v[112:113], v[44:45] op_sel:[1,0,0]
	v_pk_fma_f32 v[46:47], v[58:59], v[114:115], v[46:47] op_sel:[1,0,0]
	v_pk_fma_f32 v[48:49], v[58:59], v[116:117], v[48:49] op_sel:[1,0,0]
	v_pk_fma_f32 v[50:51], v[58:59], v[118:119], v[50:51] op_sel:[1,0,0]
	v_pk_fma_f32 v[36:37], v[58:59], v[120:121], v[36:37] op_sel:[1,0,0]
	ds_read_b128 v[106:109], v57 offset:4288
	ds_read_b128 v[110:113], v57 offset:4304
	ds_read_b128 v[114:117], v57 offset:4320
	ds_read_b128 v[118:121], v57 offset:4336
	s_waitcnt vmcnt(61) lgkmcnt(4)
	v_pk_fma_f32 v[38:39], v[60:61], v[90:91], v[38:39] op_sel_hi:[0,1,1]
	v_pk_fma_f32 v[40:41], v[60:61], v[92:93], v[40:41] op_sel_hi:[0,1,1]
	v_pk_fma_f32 v[42:43], v[60:61], v[94:95], v[42:43] op_sel_hi:[0,1,1]
	v_pk_fma_f32 v[44:45], v[60:61], v[96:97], v[44:45] op_sel_hi:[0,1,1]
	v_pk_fma_f32 v[46:47], v[60:61], v[98:99], v[46:47] op_sel_hi:[0,1,1]
	v_pk_fma_f32 v[48:49], v[60:61], v[100:101], v[48:49] op_sel_hi:[0,1,1]
	v_pk_fma_f32 v[50:51], v[60:61], v[102:103], v[50:51] op_sel_hi:[0,1,1]
	v_pk_fma_f32 v[36:37], v[60:61], v[104:105], v[36:37] op_sel_hi:[0,1,1]
	ds_read_b128 v[90:93], v57 offset:4352
	ds_read_b128 v[94:97], v57 offset:4368
	ds_read_b128 v[98:101], v57 offset:4384
	ds_read_b128 v[102:105], v57 offset:4400
	s_waitcnt vmcnt(60) lgkmcnt(4)
	v_pk_fma_f32 v[38:39], v[60:61], v[106:107], v[38:39] op_sel:[1,0,0]
	v_pk_fma_f32 v[40:41], v[60:61], v[108:109], v[40:41] op_sel:[1,0,0]
	v_pk_fma_f32 v[42:43], v[60:61], v[110:111], v[42:43] op_sel:[1,0,0]
	v_pk_fma_f32 v[44:45], v[60:61], v[112:113], v[44:45] op_sel:[1,0,0]
	v_pk_fma_f32 v[46:47], v[60:61], v[114:115], v[46:47] op_sel:[1,0,0]
	v_pk_fma_f32 v[48:49], v[60:61], v[116:117], v[48:49] op_sel:[1,0,0]
	v_pk_fma_f32 v[50:51], v[60:61], v[118:119], v[50:51] op_sel:[1,0,0]
	v_pk_fma_f32 v[36:37], v[60:61], v[120:121], v[36:37] op_sel:[1,0,0]
	ds_read_b128 v[106:109], v57 offset:4416
	ds_read_b128 v[110:113], v57 offset:4432
	ds_read_b128 v[114:117], v57 offset:4448
	ds_read_b128 v[118:121], v57 offset:4464
	s_waitcnt vmcnt(59) lgkmcnt(4)
	v_pk_fma_f32 v[38:39], v[62:63], v[90:91], v[38:39] op_sel_hi:[0,1,1]
	v_pk_fma_f32 v[40:41], v[62:63], v[92:93], v[40:41] op_sel_hi:[0,1,1]
	v_pk_fma_f32 v[42:43], v[62:63], v[94:95], v[42:43] op_sel_hi:[0,1,1]
	v_pk_fma_f32 v[44:45], v[62:63], v[96:97], v[44:45] op_sel_hi:[0,1,1]
	v_pk_fma_f32 v[46:47], v[62:63], v[98:99], v[46:47] op_sel_hi:[0,1,1]
	v_pk_fma_f32 v[48:49], v[62:63], v[100:101], v[48:49] op_sel_hi:[0,1,1]
	v_pk_fma_f32 v[50:51], v[62:63], v[102:103], v[50:51] op_sel_hi:[0,1,1]
	v_pk_fma_f32 v[36:37], v[62:63], v[104:105], v[36:37] op_sel_hi:[0,1,1]
	ds_read_b128 v[90:93], v57 offset:4480
	ds_read_b128 v[94:97], v57 offset:4496
	ds_read_b128 v[98:101], v57 offset:4512
	ds_read_b128 v[102:105], v57 offset:4528
	s_waitcnt vmcnt(58) lgkmcnt(4)
; #define LAS __attribute__((address_space(3)))
; __device__ __forceinline__ void phase_prep(const Args& a, LAS unsigned char* lds) {
;     ...
;             for (int k = kbeg; k < kbeg + 128; ++k) { const float wv = w[(size_t)k * 6144];
;                 const LAS f32x4* s4 = (const LAS f32x4*)(sc + k * 16);
; #pragma unroll
;                 for (int q = 0; q < 4; ++q) { const f32x4 s = s4[q]; acc[4 * q] += s[0] * wv; acc[4 * q + 1] += s[1] * wv; acc[4 * q + 2] += s[2] * wv; acc[4 * q + 3] += s[3] * wv; } }
	v_pk_fma_f32 v[38:39], v[62:63], v[106:107], v[38:39] op_sel:[1,0,0]
	v_pk_fma_f32 v[40:41], v[62:63], v[108:109], v[40:41] op_sel:[1,0,0]
	v_pk_fma_f32 v[42:43], v[62:63], v[110:111], v[42:43] op_sel:[1,0,0]
	v_pk_fma_f32 v[44:45], v[62:63], v[112:113], v[44:45] op_sel:[1,0,0]
	v_pk_fma_f32 v[46:47], v[62:63], v[114:115], v[46:47] op_sel:[1,0,0]
	v_pk_fma_f32 v[48:49], v[62:63], v[116:117], v[48:49] op_sel:[1,0,0]
	v_pk_fma_f32 v[50:51], v[62:63], v[118:119], v[50:51] op_sel:[1,0,0]
	v_pk_fma_f32 v[36:37], v[62:63], v[120:121], v[36:37] op_sel:[1,0,0]
	ds_read_b128 v[106:109], v57 offset:4544
	ds_read_b128 v[110:113], v57 offset:4560
	ds_read_b128 v[114:117], v57 offset:4576
	ds_read_b128 v[118:121], v57 offset:4592
	s_waitcnt vmcnt(57) lgkmcnt(4)
	v_pk_fma_f32 v[38:39], v[64:65], v[90:91], v[38:39] op_sel_hi:[0,1,1]
	v_pk_fma_f32 v[40:41], v[64:65], v[92:93], v[40:41] op_sel_hi:[0,1,1]
	v_pk_fma_f32 v[42:43], v[64:65], v[94:95], v[42:43] op_sel_hi:[0,1,1]
	v_pk_fma_f32 v[44:45], v[64:65], v[96:97], v[44:45] op_sel_hi:[0,1,1]
	v_pk_fma_f32 v[46:47], v[64:65], v[98:99], v[46:47] op_sel_hi:[0,1,1]
	v_pk_fma_f32 v[48:49], v[64:65], v[100:101], v[48:49] op_sel_hi:[0,1,1]
	v_pk_fma_f32 v[50:51], v[64:65], v[102:103], v[50:51] op_sel_hi:[0,1,1]
	v_pk_fma_f32 v[36:37], v[64:65], v[104:105], v[36:37] op_sel_hi:[0,1,1]
	ds_read_b128 v[90:93], v57 offset:4608
	ds_read_b128 v[94:97], v57 offset:4624
	ds_read_b128 v[98:101], v57 offset:4640
	ds_read_b128 v[102:105], v57 offset:4656
	s_waitcnt vmcnt(56) lgkmcnt(4)
	v_pk_fma_f32 v[38:39], v[64:65], v[106:107], v[38:39] op_sel:[1,0,0]
	v_pk_fma_f32 v[40:41], v[64:65], v[108:109], v[40:41] op_sel:[1,0,0]
	v_pk_fma_f32 v[42:43], v[64:65], v[110:111], v[42:43] op_sel:[1,0,0]
	v_pk_fma_f32 v[44:45], v[64:65], v[112:113], v[44:45] op_sel:[1,0,0]
	v_pk_fma_f32 v[46:47], v[64:65], v[114:115], v[46:47] op_sel:[1,0,0]
	v_pk_fma_f32 v[48:49], v[64:65], v[116:117], v[48:49] op_sel:[1,0,0]
	v_pk_fma_f32 v[50:51], v[64:65], v[118:119], v[50:51] op_sel:[1,0,0]
	v_pk_fma_f32 v[36:37], v[64:65], v[120:121], v[36:37] op_sel:[1,0,0]
	ds_read_b128 v[106:109], v57 offset:4672
	ds_read_b128 v[110:113], v57 offset:4688
	ds_read_b128 v[114:117], v57 offset:4704
	ds_read_b128 v[118:121], v57 offset:4720
	s_waitcnt vmcnt(55) lgkmcnt(4)
	v_pk_fma_f32 v[38:39], v[66:67], v[90:91], v[38:39] op_sel_hi:[0,1,1]
	v_pk_fma_f32 v[40:41], v[66:67], v[92:93], v[40:41] op_sel_hi:[0,1,1]
	v_pk_fma_f32 v[42:43], v[66:67], v[94:95], v[42:43] op_sel_hi:[0,1,1]
	v_pk_fma_f32 v[44:45], v[66:67], v[96:97], v[44:45] op_sel_hi:[0,1,1]
	v_pk_fma_f32 v[46:47], v[66:67], v[98:99], v[46:47] op_sel_hi:[0,1,1]
	v_pk_fma_f32 v[48:49], v[66:67], v[100:101], v[48:49] op_sel_hi:[0,1,1]
	v_pk_fma_f32 v[50:51], v[66:67], v[102:103], v[50:51] op_sel_hi:[0,1,1]
	v_pk_fma_f32 v[36:37], v[66:67], v[104:105], v[36:37] op_sel_hi:[0,1,1]
	ds_read_b128 v[90:93], v57 offset:4736
	ds_read_b128 v[94:97], v57 offset:4752
	ds_read_b128 v[98:101], v57 offset:4768
	ds_read_b128 v[102:105], v57 offset:4784
	s_waitcnt vmcnt(54) lgkmcnt(4)
	v_pk_fma_f32 v[38:39], v[66:67], v[106:107], v[38:39] op_sel:[1,0,0]
	v_pk_fma_f32 v[40:41], v[66:67], v[108:109], v[40:41] op_sel:[1,0,0]
	v_pk_fma_f32 v[42:43], v[66:67], v[110:111], v[42:43] op_sel:[1,0,0]
	v_pk_fma_f32 v[44:45], v[66:67], v[112:113], v[44:45] op_sel:[1,0,0]
	v_pk_fma_f32 v[46:47], v[66:67], v[114:115], v[46:47] op_sel:[1,0,0]
	v_pk_fma_f32 v[48:49], v[66:67], v[116:117], v[48:49] op_sel:[1,0,0]
	v_pk_fma_f32 v[50:51], v[66:67], v[118:119], v[50:51] op_sel:[1,0,0]
	v_pk_fma_f32 v[36:37], v[66:67], v[120:121], v[36:37] op_sel:[1,0,0]
	ds_read_b128 v[106:109], v57 offset:4800
	ds_read_b128 v[110:113], v57 offset:4816
	ds_read_b128 v[114:117], v57 offset:4832
	ds_read_b128 v[118:121], v57 offset:4848
	s_waitcnt vmcnt(53) lgkmcnt(4)
	v_pk_fma_f32 v[38:39], v[68:69], v[90:91], v[38:39] op_sel_hi:[0,1,1]
	v_pk_fma_f32 v[40:41], v[68:69], v[92:93], v[40:41] op_sel_hi:[0,1,1]
	v_pk_fma_f32 v[42:43], v[68:69], v[94:95], v[42:43] op_sel_hi:[0,1,1]
	v_pk_fma_f32 v[44:45], v[68:69], v[96:97], v[44:45] op_sel_hi:[0,1,1]
	v_pk_fma_f32 v[46:47], v[68:69], v[98:99], v[46:47] op_sel_hi:[0,1,1]
	v_pk_fma_f32 v[48:49], v[68:69], v[100:101], v[48:49] op_sel_hi:[0,1,1]
	v_pk_fma_f32 v[50:51], v[68:69], v[102:103], v[50:51] op_sel_hi:[0,1,1]
	v_pk_fma_f32 v[36:37], v[68:69], v[104:105], v[36:37] op_sel_hi:[0,1,1]
	ds_read_b128 v[90:93], v57 offset:4864
	ds_read_b128 v[94:97], v57 offset:4880
	ds_read_b128 v[98:101], v57 offset:4896
	ds_read_b128 v[102:105], v57 offset:4912
	s_waitcnt vmcnt(52) lgkmcnt(4)
	v_pk_fma_f32 v[38:39], v[68:69], v[106:107], v[38:39] op_sel:[1,0,0]
	v_pk_fma_f32 v[40:41], v[68:69], v[108:109], v[40:41] op_sel:[1,0,0]
	v_pk_fma_f32 v[42:43], v[68:69], v[110:111], v[42:43] op_sel:[1,0,0]
	v_pk_fma_f32 v[44:45], v[68:69], v[112:113], v[44:45] op_sel:[1,0,0]
	v_pk_fma_f32 v[46:47], v[68:69], v[114:115], v[46:47] op_sel:[1,0,0]
	v_pk_fma_f32 v[48:49], v[68:69], v[116:117], v[48:49] op_sel:[1,0,0]
	v_pk_fma_f32 v[50:51], v[68:69], v[118:119], v[50:51] op_sel:[1,0,0]
	v_pk_fma_f32 v[36:37], v[68:69], v[120:121], v[36:37] op_sel:[1,0,0]
	ds_read_b128 v[106:109], v57 offset:4928
	ds_read_b128 v[110:113], v57 offset:4944
	ds_read_b128 v[114:117], v57 offset:4960
	ds_read_b128 v[118:121], v57 offset:4976
	s_waitcnt vmcnt(51) lgkmcnt(4)
; #define LAS __attribute__((address_space(3)))
; __device__ __forceinline__ void phase_prep(const Args& a, LAS unsigned char* lds) {
;     ...
;             for (int k = kbeg; k < kbeg + 128; ++k) { const float wv = w[(size_t)k * 6144];
;                 const LAS f32x4* s4 = (const LAS f32x4*)(sc + k * 16);
; #pragma unroll
;                 for (int q = 0; q < 4; ++q) { const f32x4 s = s4[q]; acc[4 * q] += s[0] * wv; acc[4 * q + 1] += s[1] * wv; acc[4 * q + 2] += s[2] * wv; acc[4 * q + 3] += s[3] * wv; } }
	v_pk_fma_f32 v[38:39], v[70:71], v[90:91], v[38:39] op_sel_hi:[0,1,1]
	v_pk_fma_f32 v[40:41], v[70:71], v[92:93], v[40:41] op_sel_hi:[0,1,1]
	v_pk_fma_f32 v[42:43], v[70:71], v[94:95], v[42:43] op_sel_hi:[0,1,1]
	v_pk_fma_f32 v[44:45], v[70:71], v[96:97], v[44:45] op_sel_hi:[0,1,1]
	v_pk_fma_f32 v[46:47], v[70:71], v[98:99], v[46:47] op_sel_hi:[0,1,1]
	v_pk_fma_f32 v[48:49], v[70:71], v[100:101], v[48:49] op_sel_hi:[0,1,1]
	v_pk_fma_f32 v[50:51], v[70:71], v[102:103], v[50:51] op_sel_hi:[0,1,1]
	v_pk_fma_f32 v[36:37], v[70:71], v[104:105], v[36:37] op_sel_hi:[0,1,1]
	ds_read_b128 v[90:93], v57 offset:4992
	ds_read_b128 v[94:97], v57 offset:5008
	ds_read_b128 v[98:101], v57 offset:5024
	ds_read_b128 v[102:105], v57 offset:5040
	s_waitcnt vmcnt(50) lgkmcnt(4)
	v_pk_fma_f32 v[38:39], v[70:71], v[106:107], v[38:39] op_sel:[1,0,0]
	v_pk_fma_f32 v[40:41], v[70:71], v[108:109], v[40:41] op_sel:[1,0,0]
	v_pk_fma_f32 v[42:43], v[70:71], v[110:111], v[42:43] op_sel:[1,0,0]
	v_pk_fma_f32 v[44:45], v[70:71], v[112:113], v[44:45] op_sel:[1,0,0]
	v_pk_fma_f32 v[46:47], v[70:71], v[114:115], v[46:47] op_sel:[1,0,0]
	v_pk_fma_f32 v[48:49], v[70:71], v[116:117], v[48:49] op_sel:[1,0,0]
	v_pk_fma_f32 v[50:51], v[70:71], v[118:119], v[50:51] op_sel:[1,0,0]
	v_pk_fma_f32 v[36:37], v[70:71], v[120:121], v[36:37] op_sel:[1,0,0]
	ds_read_b128 v[106:109], v57 offset:5056
	ds_read_b128 v[110:113], v57 offset:5072
	ds_read_b128 v[114:117], v57 offset:5088
	ds_read_b128 v[118:121], v57 offset:5104
	s_waitcnt vmcnt(49) lgkmcnt(4)
	v_pk_fma_f32 v[38:39], v[72:73], v[90:91], v[38:39] op_sel_hi:[0,1,1]
	v_pk_fma_f32 v[40:41], v[72:73], v[92:93], v[40:41] op_sel_hi:[0,1,1]
	v_pk_fma_f32 v[42:43], v[72:73], v[94:95], v[42:43] op_sel_hi:[0,1,1]
	v_pk_fma_f32 v[44:45], v[72:73], v[96:97], v[44:45] op_sel_hi:[0,1,1]
	v_pk_fma_f32 v[46:47], v[72:73], v[98:99], v[46:47] op_sel_hi:[0,1,1]
	v_pk_fma_f32 v[48:49], v[72:73], v[100:101], v[48:49] op_sel_hi:[0,1,1]
	v_pk_fma_f32 v[50:51], v[72:73], v[102:103], v[50:51] op_sel_hi:[0,1,1]
	v_pk_fma_f32 v[36:37], v[72:73], v[104:105], v[36:37] op_sel_hi:[0,1,1]
	ds_read_b128 v[90:93], v57 offset:5120
	ds_read_b128 v[94:97], v57 offset:5136
	ds_read_b128 v[98:101], v57 offset:5152
	ds_read_b128 v[102:105], v57 offset:5168
	s_waitcnt vmcnt(48) lgkmcnt(4)
	v_pk_fma_f32 v[38:39], v[72:73], v[106:107], v[38:39] op_sel:[1,0,0]
	v_pk_fma_f32 v[40:41], v[72:73], v[108:109], v[40:41] op_sel:[1,0,0]
	v_pk_fma_f32 v[42:43], v[72:73], v[110:111], v[42:43] op_sel:[1,0,0]
	v_pk_fma_f32 v[44:45], v[72:73], v[112:113], v[44:45] op_sel:[1,0,0]
	v_pk_fma_f32 v[46:47], v[72:73], v[114:115], v[46:47] op_sel:[1,0,0]
	v_pk_fma_f32 v[48:49], v[72:73], v[116:117], v[48:49] op_sel:[1,0,0]
	v_pk_fma_f32 v[50:51], v[72:73], v[118:119], v[50:51] op_sel:[1,0,0]
	v_pk_fma_f32 v[36:37], v[72:73], v[120:121], v[36:37] op_sel:[1,0,0]
	ds_read_b128 v[106:109], v57 offset:5184
	ds_read_b128 v[110:113], v57 offset:5200
	ds_read_b128 v[114:117], v57 offset:5216
	ds_read_b128 v[118:121], v57 offset:5232
	s_waitcnt vmcnt(47) lgkmcnt(4)
	v_pk_fma_f32 v[38:39], v[74:75], v[90:91], v[38:39] op_sel_hi:[0,1,1]
	v_pk_fma_f32 v[40:41], v[74:75], v[92:93], v[40:41] op_sel_hi:[0,1,1]
	v_pk_fma_f32 v[42:43], v[74:75], v[94:95], v[42:43] op_sel_hi:[0,1,1]
	v_pk_fma_f32 v[44:45], v[74:75], v[96:97], v[44:45] op_sel_hi:[0,1,1]
	v_pk_fma_f32 v[46:47], v[74:75], v[98:99], v[46:47] op_sel_hi:[0,1,1]
	v_pk_fma_f32 v[48:49], v[74:75], v[100:101], v[48:49] op_sel_hi:[0,1,1]
	v_pk_fma_f32 v[50:51], v[74:75], v[102:103], v[50:51] op_sel_hi:[0,1,1]
	v_pk_fma_f32 v[36:37], v[74:75], v[104:105], v[36:37] op_sel_hi:[0,1,1]
	ds_read_b128 v[90:93], v57 offset:5248
	ds_read_b128 v[94:97], v57 offset:5264
	ds_read_b128 v[98:101], v57 offset:5280
	ds_read_b128 v[102:105], v57 offset:5296
	s_waitcnt vmcnt(46) lgkmcnt(4)
	v_pk_fma_f32 v[38:39], v[74:75], v[106:107], v[38:39] op_sel:[1,0,0]
	v_pk_fma_f32 v[40:41], v[74:75], v[108:109], v[40:41] op_sel:[1,0,0]
	v_pk_fma_f32 v[42:43], v[74:75], v[110:111], v[42:43] op_sel:[1,0,0]
	v_pk_fma_f32 v[44:45], v[74:75], v[112:113], v[44:45] op_sel:[1,0,0]
	v_pk_fma_f32 v[46:47], v[74:75], v[114:115], v[46:47] op_sel:[1,0,0]
	v_pk_fma_f32 v[48:49], v[74:75], v[116:117], v[48:49] op_sel:[1,0,0]
	v_pk_fma_f32 v[50:51], v[74:75], v[118:119], v[50:51] op_sel:[1,0,0]
	v_pk_fma_f32 v[36:37], v[74:75], v[120:121], v[36:37] op_sel:[1,0,0]
	ds_read_b128 v[106:109], v57 offset:5312
	ds_read_b128 v[110:113], v57 offset:5328
	ds_read_b128 v[114:117], v57 offset:5344
	ds_read_b128 v[118:121], v57 offset:5360
	s_waitcnt vmcnt(45) lgkmcnt(4)
	v_pk_fma_f32 v[38:39], v[76:77], v[90:91], v[38:39] op_sel_hi:[0,1,1]
	v_pk_fma_f32 v[40:41], v[76:77], v[92:93], v[40:41] op_sel_hi:[0,1,1]
	v_pk_fma_f32 v[42:43], v[76:77], v[94:95], v[42:43] op_sel_hi:[0,1,1]
	v_pk_fma_f32 v[44:45], v[76:77], v[96:97], v[44:45] op_sel_hi:[0,1,1]
	v_pk_fma_f32 v[46:47], v[76:77], v[98:99], v[46:47] op_sel_hi:[0,1,1]
	v_pk_fma_f32 v[48:49], v[76:77], v[100:101], v[48:49] op_sel_hi:[0,1,1]
	v_pk_fma_f32 v[50:51], v[76:77], v[102:103], v[50:51] op_sel_hi:[0,1,1]
	v_pk_fma_f32 v[36:37], v[76:77], v[104:105], v[36:37] op_sel_hi:[0,1,1]
	ds_read_b128 v[90:93], v57 offset:5376
	ds_read_b128 v[94:97], v57 offset:5392
	ds_read_b128 v[98:101], v57 offset:5408
	ds_read_b128 v[102:105], v57 offset:5424
	s_waitcnt vmcnt(44) lgkmcnt(4)
; #define LAS __attribute__((address_space(3)))
; __device__ __forceinline__ void phase_prep(const Args& a, LAS unsigned char* lds) {
;     ...
;             for (int k = kbeg; k < kbeg + 128; ++k) { const float wv = w[(size_t)k * 6144];
;                 const LAS f32x4* s4 = (const LAS f32x4*)(sc + k * 16);
; #pragma unroll
;                 for (int q = 0; q < 4; ++q) { const f32x4 s = s4[q]; acc[4 * q] += s[0] * wv; acc[4 * q + 1] += s[1] * wv; acc[4 * q + 2] += s[2] * wv; acc[4 * q + 3] += s[3] * wv; } }
	v_pk_fma_f32 v[38:39], v[76:77], v[106:107], v[38:39] op_sel:[1,0,0]
	v_pk_fma_f32 v[40:41], v[76:77], v[108:109], v[40:41] op_sel:[1,0,0]
	v_pk_fma_f32 v[42:43], v[76:77], v[110:111], v[42:43] op_sel:[1,0,0]
	v_pk_fma_f32 v[44:45], v[76:77], v[112:113], v[44:45] op_sel:[1,0,0]
	v_pk_fma_f32 v[46:47], v[76:77], v[114:115], v[46:47] op_sel:[1,0,0]
	v_pk_fma_f32 v[48:49], v[76:77], v[116:117], v[48:49] op_sel:[1,0,0]
	v_pk_fma_f32 v[50:51], v[76:77], v[118:119], v[50:51] op_sel:[1,0,0]
	v_pk_fma_f32 v[36:37], v[76:77], v[120:121], v[36:37] op_sel:[1,0,0]
	ds_read_b128 v[106:109], v57 offset:5440
	ds_read_b128 v[110:113], v57 offset:5456
	ds_read_b128 v[114:117], v57 offset:5472
	ds_read_b128 v[118:121], v57 offset:5488
	s_waitcnt vmcnt(43) lgkmcnt(4)
	v_pk_fma_f32 v[38:39], v[78:79], v[90:91], v[38:39] op_sel_hi:[0,1,1]
	v_pk_fma_f32 v[40:41], v[78:79], v[92:93], v[40:41] op_sel_hi:[0,1,1]
	v_pk_fma_f32 v[42:43], v[78:79], v[94:95], v[42:43] op_sel_hi:[0,1,1]
	v_pk_fma_f32 v[44:45], v[78:79], v[96:97], v[44:45] op_sel_hi:[0,1,1]
	v_pk_fma_f32 v[46:47], v[78:79], v[98:99], v[46:47] op_sel_hi:[0,1,1]
	v_pk_fma_f32 v[48:49], v[78:79], v[100:101], v[48:49] op_sel_hi:[0,1,1]
	v_pk_fma_f32 v[50:51], v[78:79], v[102:103], v[50:51] op_sel_hi:[0,1,1]
	v_pk_fma_f32 v[36:37], v[78:79], v[104:105], v[36:37] op_sel_hi:[0,1,1]
	ds_read_b128 v[90:93], v57 offset:5504
	ds_read_b128 v[94:97], v57 offset:5520
	ds_read_b128 v[98:101], v57 offset:5536
	ds_read_b128 v[102:105], v57 offset:5552
	s_waitcnt vmcnt(42) lgkmcnt(4)
	v_pk_fma_f32 v[38:39], v[78:79], v[106:107], v[38:39] op_sel:[1,0,0]
	v_pk_fma_f32 v[40:41], v[78:79], v[108:109], v[40:41] op_sel:[1,0,0]
	v_pk_fma_f32 v[42:43], v[78:79], v[110:111], v[42:43] op_sel:[1,0,0]
	v_pk_fma_f32 v[44:45], v[78:79], v[112:113], v[44:45] op_sel:[1,0,0]
	v_pk_fma_f32 v[46:47], v[78:79], v[114:115], v[46:47] op_sel:[1,0,0]
	v_pk_fma_f32 v[48:49], v[78:79], v[116:117], v[48:49] op_sel:[1,0,0]
	v_pk_fma_f32 v[50:51], v[78:79], v[118:119], v[50:51] op_sel:[1,0,0]
	v_pk_fma_f32 v[36:37], v[78:79], v[120:121], v[36:37] op_sel:[1,0,0]
	ds_read_b128 v[106:109], v57 offset:5568
	ds_read_b128 v[110:113], v57 offset:5584
	ds_read_b128 v[114:117], v57 offset:5600
	ds_read_b128 v[118:121], v57 offset:5616
	s_waitcnt vmcnt(41) lgkmcnt(4)
	v_pk_fma_f32 v[38:39], v[80:81], v[90:91], v[38:39] op_sel_hi:[0,1,1]
	v_pk_fma_f32 v[40:41], v[80:81], v[92:93], v[40:41] op_sel_hi:[0,1,1]
	v_pk_fma_f32 v[42:43], v[80:81], v[94:95], v[42:43] op_sel_hi:[0,1,1]
	v_pk_fma_f32 v[44:45], v[80:81], v[96:97], v[44:45] op_sel_hi:[0,1,1]
	v_pk_fma_f32 v[46:47], v[80:81], v[98:99], v[46:47] op_sel_hi:[0,1,1]
	v_pk_fma_f32 v[48:49], v[80:81], v[100:101], v[48:49] op_sel_hi:[0,1,1]
	v_pk_fma_f32 v[50:51], v[80:81], v[102:103], v[50:51] op_sel_hi:[0,1,1]
	v_pk_fma_f32 v[36:37], v[80:81], v[104:105], v[36:37] op_sel_hi:[0,1,1]
	ds_read_b128 v[90:93], v57 offset:5632
	ds_read_b128 v[94:97], v57 offset:5648
	ds_read_b128 v[98:101], v57 offset:5664
	ds_read_b128 v[102:105], v57 offset:5680
	s_waitcnt vmcnt(40) lgkmcnt(4)
	v_pk_fma_f32 v[38:39], v[80:81], v[106:107], v[38:39] op_sel:[1,0,0]
	v_pk_fma_f32 v[40:41], v[80:81], v[108:109], v[40:41] op_sel:[1,0,0]
	v_pk_fma_f32 v[42:43], v[80:81], v[110:111], v[42:43] op_sel:[1,0,0]
	v_pk_fma_f32 v[44:45], v[80:81], v[112:113], v[44:45] op_sel:[1,0,0]
	v_pk_fma_f32 v[46:47], v[80:81], v[114:115], v[46:47] op_sel:[1,0,0]
	v_pk_fma_f32 v[48:49], v[80:81], v[116:117], v[48:49] op_sel:[1,0,0]
	v_pk_fma_f32 v[50:51], v[80:81], v[118:119], v[50:51] op_sel:[1,0,0]
	v_pk_fma_f32 v[36:37], v[80:81], v[120:121], v[36:37] op_sel:[1,0,0]
	ds_read_b128 v[106:109], v57 offset:5696
	ds_read_b128 v[110:113], v57 offset:5712
	ds_read_b128 v[114:117], v57 offset:5728
	ds_read_b128 v[118:121], v57 offset:5744
	s_waitcnt vmcnt(39) lgkmcnt(4)
	v_pk_fma_f32 v[38:39], v[82:83], v[90:91], v[38:39] op_sel_hi:[0,1,1]
	v_pk_fma_f32 v[40:41], v[82:83], v[92:93], v[40:41] op_sel_hi:[0,1,1]
	v_pk_fma_f32 v[42:43], v[82:83], v[94:95], v[42:43] op_sel_hi:[0,1,1]
	v_pk_fma_f32 v[44:45], v[82:83], v[96:97], v[44:45] op_sel_hi:[0,1,1]
	v_pk_fma_f32 v[46:47], v[82:83], v[98:99], v[46:47] op_sel_hi:[0,1,1]
	v_pk_fma_f32 v[48:49], v[82:83], v[100:101], v[48:49] op_sel_hi:[0,1,1]
	v_pk_fma_f32 v[50:51], v[82:83], v[102:103], v[50:51] op_sel_hi:[0,1,1]
	v_pk_fma_f32 v[36:37], v[82:83], v[104:105], v[36:37] op_sel_hi:[0,1,1]
	ds_read_b128 v[90:93], v57 offset:5760
	ds_read_b128 v[94:97], v57 offset:5776
	ds_read_b128 v[98:101], v57 offset:5792
	ds_read_b128 v[102:105], v57 offset:5808
	s_waitcnt vmcnt(38) lgkmcnt(4)
	v_pk_fma_f32 v[38:39], v[82:83], v[106:107], v[38:39] op_sel:[1,0,0]
	v_pk_fma_f32 v[40:41], v[82:83], v[108:109], v[40:41] op_sel:[1,0,0]
	v_pk_fma_f32 v[42:43], v[82:83], v[110:111], v[42:43] op_sel:[1,0,0]
	v_pk_fma_f32 v[44:45], v[82:83], v[112:113], v[44:45] op_sel:[1,0,0]
	v_pk_fma_f32 v[46:47], v[82:83], v[114:115], v[46:47] op_sel:[1,0,0]
	v_pk_fma_f32 v[48:49], v[82:83], v[116:117], v[48:49] op_sel:[1,0,0]
	v_pk_fma_f32 v[50:51], v[82:83], v[118:119], v[50:51] op_sel:[1,0,0]
	v_pk_fma_f32 v[36:37], v[82:83], v[120:121], v[36:37] op_sel:[1,0,0]
	ds_read_b128 v[106:109], v57 offset:5824
	ds_read_b128 v[110:113], v57 offset:5840
	ds_read_b128 v[114:117], v57 offset:5856
	ds_read_b128 v[118:121], v57 offset:5872
	s_waitcnt vmcnt(37) lgkmcnt(4)
; #define LAS __attribute__((address_space(3)))
; __device__ __forceinline__ void phase_prep(const Args& a, LAS unsigned char* lds) {
;     ...
;             for (int k = kbeg; k < kbeg + 128; ++k) { const float wv = w[(size_t)k * 6144];
;                 const LAS f32x4* s4 = (const LAS f32x4*)(sc + k * 16);
; #pragma unroll
;                 for (int q = 0; q < 4; ++q) { const f32x4 s = s4[q]; acc[4 * q] += s[0] * wv; acc[4 * q + 1] += s[1] * wv; acc[4 * q + 2] += s[2] * wv; acc[4 * q + 3] += s[3] * wv; } }
	v_pk_fma_f32 v[38:39], v[84:85], v[90:91], v[38:39] op_sel_hi:[0,1,1]
	v_pk_fma_f32 v[40:41], v[84:85], v[92:93], v[40:41] op_sel_hi:[0,1,1]
	v_pk_fma_f32 v[42:43], v[84:85], v[94:95], v[42:43] op_sel_hi:[0,1,1]
	v_pk_fma_f32 v[44:45], v[84:85], v[96:97], v[44:45] op_sel_hi:[0,1,1]
	v_pk_fma_f32 v[46:47], v[84:85], v[98:99], v[46:47] op_sel_hi:[0,1,1]
	v_pk_fma_f32 v[48:49], v[84:85], v[100:101], v[48:49] op_sel_hi:[0,1,1]
	v_pk_fma_f32 v[50:51], v[84:85], v[102:103], v[50:51] op_sel_hi:[0,1,1]
	v_pk_fma_f32 v[36:37], v[84:85], v[104:105], v[36:37] op_sel_hi:[0,1,1]
	ds_read_b128 v[90:93], v57 offset:5888
	ds_read_b128 v[94:97], v57 offset:5904
	ds_read_b128 v[98:101], v57 offset:5920
	ds_read_b128 v[102:105], v57 offset:5936
	s_waitcnt vmcnt(36) lgkmcnt(4)
	v_pk_fma_f32 v[38:39], v[84:85], v[106:107], v[38:39] op_sel:[1,0,0]
	v_pk_fma_f32 v[40:41], v[84:85], v[108:109], v[40:41] op_sel:[1,0,0]
	v_pk_fma_f32 v[42:43], v[84:85], v[110:111], v[42:43] op_sel:[1,0,0]
	v_pk_fma_f32 v[44:45], v[84:85], v[112:113], v[44:45] op_sel:[1,0,0]
	v_pk_fma_f32 v[46:47], v[84:85], v[114:115], v[46:47] op_sel:[1,0,0]
	v_pk_fma_f32 v[48:49], v[84:85], v[116:117], v[48:49] op_sel:[1,0,0]
	v_pk_fma_f32 v[50:51], v[84:85], v[118:119], v[50:51] op_sel:[1,0,0]
	v_pk_fma_f32 v[36:37], v[84:85], v[120:121], v[36:37] op_sel:[1,0,0]
	ds_read_b128 v[106:109], v57 offset:5952
	ds_read_b128 v[110:113], v57 offset:5968
	ds_read_b128 v[114:117], v57 offset:5984
	ds_read_b128 v[118:121], v57 offset:6000
	s_waitcnt vmcnt(35) lgkmcnt(4)
	v_pk_fma_f32 v[38:39], v[86:87], v[90:91], v[38:39] op_sel_hi:[0,1,1]
	v_pk_fma_f32 v[40:41], v[86:87], v[92:93], v[40:41] op_sel_hi:[0,1,1]
	v_pk_fma_f32 v[42:43], v[86:87], v[94:95], v[42:43] op_sel_hi:[0,1,1]
	v_pk_fma_f32 v[44:45], v[86:87], v[96:97], v[44:45] op_sel_hi:[0,1,1]
	v_pk_fma_f32 v[46:47], v[86:87], v[98:99], v[46:47] op_sel_hi:[0,1,1]
	v_pk_fma_f32 v[48:49], v[86:87], v[100:101], v[48:49] op_sel_hi:[0,1,1]
	v_pk_fma_f32 v[50:51], v[86:87], v[102:103], v[50:51] op_sel_hi:[0,1,1]
	v_pk_fma_f32 v[36:37], v[86:87], v[104:105], v[36:37] op_sel_hi:[0,1,1]
	ds_read_b128 v[90:93], v57 offset:6016
	ds_read_b128 v[94:97], v57 offset:6032
	ds_read_b128 v[98:101], v57 offset:6048
	ds_read_b128 v[102:105], v57 offset:6064
	s_waitcnt vmcnt(34) lgkmcnt(4)
	v_pk_fma_f32 v[38:39], v[86:87], v[106:107], v[38:39] op_sel:[1,0,0]
	v_pk_fma_f32 v[40:41], v[86:87], v[108:109], v[40:41] op_sel:[1,0,0]
	v_pk_fma_f32 v[42:43], v[86:87], v[110:111], v[42:43] op_sel:[1,0,0]
	v_pk_fma_f32 v[44:45], v[86:87], v[112:113], v[44:45] op_sel:[1,0,0]
	v_pk_fma_f32 v[46:47], v[86:87], v[114:115], v[46:47] op_sel:[1,0,0]
	v_pk_fma_f32 v[48:49], v[86:87], v[116:117], v[48:49] op_sel:[1,0,0]
	v_pk_fma_f32 v[50:51], v[86:87], v[118:119], v[50:51] op_sel:[1,0,0]
	v_pk_fma_f32 v[36:37], v[86:87], v[120:121], v[36:37] op_sel:[1,0,0]
	ds_read_b128 v[106:109], v57 offset:6080
	ds_read_b128 v[110:113], v57 offset:6096
	ds_read_b128 v[114:117], v57 offset:6112
	ds_read_b128 v[118:121], v57 offset:6128
	s_waitcnt vmcnt(33) lgkmcnt(4)
	v_pk_fma_f32 v[38:39], v[88:89], v[90:91], v[38:39] op_sel_hi:[0,1,1]
	v_pk_fma_f32 v[40:41], v[88:89], v[92:93], v[40:41] op_sel_hi:[0,1,1]
	v_pk_fma_f32 v[42:43], v[88:89], v[94:95], v[42:43] op_sel_hi:[0,1,1]
	v_pk_fma_f32 v[44:45], v[88:89], v[96:97], v[44:45] op_sel_hi:[0,1,1]
	v_pk_fma_f32 v[46:47], v[88:89], v[98:99], v[46:47] op_sel_hi:[0,1,1]
	v_pk_fma_f32 v[48:49], v[88:89], v[100:101], v[48:49] op_sel_hi:[0,1,1]
	v_pk_fma_f32 v[50:51], v[88:89], v[102:103], v[50:51] op_sel_hi:[0,1,1]
	v_pk_fma_f32 v[36:37], v[88:89], v[104:105], v[36:37] op_sel_hi:[0,1,1]
	ds_read_b128 v[90:93], v57 offset:6144
	ds_read_b128 v[94:97], v57 offset:6160
	ds_read_b128 v[98:101], v57 offset:6176
	ds_read_b128 v[102:105], v57 offset:6192
	s_waitcnt vmcnt(32) lgkmcnt(4)
	v_pk_fma_f32 v[38:39], v[88:89], v[106:107], v[38:39] op_sel:[1,0,0]
	v_pk_fma_f32 v[40:41], v[88:89], v[108:109], v[40:41] op_sel:[1,0,0]
	v_pk_fma_f32 v[42:43], v[88:89], v[110:111], v[42:43] op_sel:[1,0,0]
	v_pk_fma_f32 v[44:45], v[88:89], v[112:113], v[44:45] op_sel:[1,0,0]
	v_pk_fma_f32 v[46:47], v[88:89], v[114:115], v[46:47] op_sel:[1,0,0]
	v_pk_fma_f32 v[48:49], v[88:89], v[116:117], v[48:49] op_sel:[1,0,0]
	v_pk_fma_f32 v[50:51], v[88:89], v[118:119], v[50:51] op_sel:[1,0,0]
	v_pk_fma_f32 v[36:37], v[88:89], v[120:121], v[36:37] op_sel:[1,0,0]
	ds_read_b128 v[106:109], v57 offset:6208
	ds_read_b128 v[110:113], v57 offset:6224
	ds_read_b128 v[114:117], v57 offset:6240
	ds_read_b128 v[118:121], v57 offset:6256
	s_waitcnt vmcnt(31) lgkmcnt(4)
	v_pk_fma_f32 v[38:39], v[122:123], v[90:91], v[38:39] op_sel_hi:[0,1,1]
	v_pk_fma_f32 v[40:41], v[122:123], v[92:93], v[40:41] op_sel_hi:[0,1,1]
	v_pk_fma_f32 v[42:43], v[122:123], v[94:95], v[42:43] op_sel_hi:[0,1,1]
	v_pk_fma_f32 v[44:45], v[122:123], v[96:97], v[44:45] op_sel_hi:[0,1,1]
	v_pk_fma_f32 v[46:47], v[122:123], v[98:99], v[46:47] op_sel_hi:[0,1,1]
	v_pk_fma_f32 v[48:49], v[122:123], v[100:101], v[48:49] op_sel_hi:[0,1,1]
	v_pk_fma_f32 v[50:51], v[122:123], v[102:103], v[50:51] op_sel_hi:[0,1,1]
	v_pk_fma_f32 v[36:37], v[122:123], v[104:105], v[36:37] op_sel_hi:[0,1,1]
	ds_read_b128 v[90:93], v57 offset:6272
	ds_read_b128 v[94:97], v57 offset:6288
	ds_read_b128 v[98:101], v57 offset:6304
	ds_read_b128 v[102:105], v57 offset:6320
	s_waitcnt vmcnt(30) lgkmcnt(4)
; #define LAS __attribute__((address_space(3)))
; __device__ __forceinline__ void phase_prep(const Args& a, LAS unsigned char* lds) {
;     ...
;             for (int k = kbeg; k < kbeg + 128; ++k) { const float wv = w[(size_t)k * 6144];
;                 const LAS f32x4* s4 = (const LAS f32x4*)(sc + k * 16);
; #pragma unroll
;                 for (int q = 0; q < 4; ++q) { const f32x4 s = s4[q]; acc[4 * q] += s[0] * wv; acc[4 * q + 1] += s[1] * wv; acc[4 * q + 2] += s[2] * wv; acc[4 * q + 3] += s[3] * wv; } }
	v_pk_fma_f32 v[38:39], v[122:123], v[106:107], v[38:39] op_sel:[1,0,0]
	v_pk_fma_f32 v[40:41], v[122:123], v[108:109], v[40:41] op_sel:[1,0,0]
	v_pk_fma_f32 v[42:43], v[122:123], v[110:111], v[42:43] op_sel:[1,0,0]
	v_pk_fma_f32 v[44:45], v[122:123], v[112:113], v[44:45] op_sel:[1,0,0]
	v_pk_fma_f32 v[46:47], v[122:123], v[114:115], v[46:47] op_sel:[1,0,0]
	v_pk_fma_f32 v[48:49], v[122:123], v[116:117], v[48:49] op_sel:[1,0,0]
	v_pk_fma_f32 v[50:51], v[122:123], v[118:119], v[50:51] op_sel:[1,0,0]
	v_pk_fma_f32 v[36:37], v[122:123], v[120:121], v[36:37] op_sel:[1,0,0]
	ds_read_b128 v[106:109], v57 offset:6336
	ds_read_b128 v[110:113], v57 offset:6352
	ds_read_b128 v[114:117], v57 offset:6368
	ds_read_b128 v[118:121], v57 offset:6384
	s_waitcnt vmcnt(29) lgkmcnt(4)
	v_pk_fma_f32 v[38:39], v[124:125], v[90:91], v[38:39] op_sel_hi:[0,1,1]
	v_pk_fma_f32 v[40:41], v[124:125], v[92:93], v[40:41] op_sel_hi:[0,1,1]
	v_pk_fma_f32 v[42:43], v[124:125], v[94:95], v[42:43] op_sel_hi:[0,1,1]
	v_pk_fma_f32 v[44:45], v[124:125], v[96:97], v[44:45] op_sel_hi:[0,1,1]
	v_pk_fma_f32 v[46:47], v[124:125], v[98:99], v[46:47] op_sel_hi:[0,1,1]
	v_pk_fma_f32 v[48:49], v[124:125], v[100:101], v[48:49] op_sel_hi:[0,1,1]
	v_pk_fma_f32 v[50:51], v[124:125], v[102:103], v[50:51] op_sel_hi:[0,1,1]
	v_pk_fma_f32 v[36:37], v[124:125], v[104:105], v[36:37] op_sel_hi:[0,1,1]
	ds_read_b128 v[90:93], v57 offset:6400
	ds_read_b128 v[94:97], v57 offset:6416
	ds_read_b128 v[98:101], v57 offset:6432
	ds_read_b128 v[102:105], v57 offset:6448
	s_waitcnt vmcnt(28) lgkmcnt(4)
	v_pk_fma_f32 v[38:39], v[124:125], v[106:107], v[38:39] op_sel:[1,0,0]
	v_pk_fma_f32 v[40:41], v[124:125], v[108:109], v[40:41] op_sel:[1,0,0]
	v_pk_fma_f32 v[42:43], v[124:125], v[110:111], v[42:43] op_sel:[1,0,0]
	v_pk_fma_f32 v[44:45], v[124:125], v[112:113], v[44:45] op_sel:[1,0,0]
	v_pk_fma_f32 v[46:47], v[124:125], v[114:115], v[46:47] op_sel:[1,0,0]
	v_pk_fma_f32 v[48:49], v[124:125], v[116:117], v[48:49] op_sel:[1,0,0]
	v_pk_fma_f32 v[50:51], v[124:125], v[118:119], v[50:51] op_sel:[1,0,0]
	v_pk_fma_f32 v[36:37], v[124:125], v[120:121], v[36:37] op_sel:[1,0,0]
	ds_read_b128 v[106:109], v57 offset:6464
	ds_read_b128 v[110:113], v57 offset:6480
	ds_read_b128 v[114:117], v57 offset:6496
	ds_read_b128 v[118:121], v57 offset:6512
	s_waitcnt vmcnt(27) lgkmcnt(4)
	v_pk_fma_f32 v[38:39], v[126:127], v[90:91], v[38:39] op_sel_hi:[0,1,1]
	v_pk_fma_f32 v[40:41], v[126:127], v[92:93], v[40:41] op_sel_hi:[0,1,1]
	v_pk_fma_f32 v[42:43], v[126:127], v[94:95], v[42:43] op_sel_hi:[0,1,1]
	v_pk_fma_f32 v[44:45], v[126:127], v[96:97], v[44:45] op_sel_hi:[0,1,1]
	v_pk_fma_f32 v[46:47], v[126:127], v[98:99], v[46:47] op_sel_hi:[0,1,1]
	v_pk_fma_f32 v[48:49], v[126:127], v[100:101], v[48:49] op_sel_hi:[0,1,1]
	v_pk_fma_f32 v[50:51], v[126:127], v[102:103], v[50:51] op_sel_hi:[0,1,1]
	v_pk_fma_f32 v[36:37], v[126:127], v[104:105], v[36:37] op_sel_hi:[0,1,1]
	ds_read_b128 v[90:93], v57 offset:6528
	ds_read_b128 v[94:97], v57 offset:6544
	ds_read_b128 v[98:101], v57 offset:6560
	ds_read_b128 v[102:105], v57 offset:6576
	s_waitcnt vmcnt(26) lgkmcnt(4)
	v_pk_fma_f32 v[38:39], v[126:127], v[106:107], v[38:39] op_sel:[1,0,0]
	v_pk_fma_f32 v[40:41], v[126:127], v[108:109], v[40:41] op_sel:[1,0,0]
	v_pk_fma_f32 v[42:43], v[126:127], v[110:111], v[42:43] op_sel:[1,0,0]
	v_pk_fma_f32 v[44:45], v[126:127], v[112:113], v[44:45] op_sel:[1,0,0]
	v_pk_fma_f32 v[46:47], v[126:127], v[114:115], v[46:47] op_sel:[1,0,0]
	v_pk_fma_f32 v[48:49], v[126:127], v[116:117], v[48:49] op_sel:[1,0,0]
	v_pk_fma_f32 v[50:51], v[126:127], v[118:119], v[50:51] op_sel:[1,0,0]
	v_pk_fma_f32 v[36:37], v[126:127], v[120:121], v[36:37] op_sel:[1,0,0]
	ds_read_b128 v[106:109], v57 offset:6592
	ds_read_b128 v[110:113], v57 offset:6608
	ds_read_b128 v[114:117], v57 offset:6624
	ds_read_b128 v[118:121], v57 offset:6640
	s_waitcnt vmcnt(25) lgkmcnt(4)
	v_pk_fma_f32 v[38:39], v[128:129], v[90:91], v[38:39] op_sel_hi:[0,1,1]
	v_pk_fma_f32 v[40:41], v[128:129], v[92:93], v[40:41] op_sel_hi:[0,1,1]
	v_pk_fma_f32 v[42:43], v[128:129], v[94:95], v[42:43] op_sel_hi:[0,1,1]
	v_pk_fma_f32 v[44:45], v[128:129], v[96:97], v[44:45] op_sel_hi:[0,1,1]
	v_pk_fma_f32 v[46:47], v[128:129], v[98:99], v[46:47] op_sel_hi:[0,1,1]
	v_pk_fma_f32 v[48:49], v[128:129], v[100:101], v[48:49] op_sel_hi:[0,1,1]
	v_pk_fma_f32 v[50:51], v[128:129], v[102:103], v[50:51] op_sel_hi:[0,1,1]
	v_pk_fma_f32 v[36:37], v[128:129], v[104:105], v[36:37] op_sel_hi:[0,1,1]
	ds_read_b128 v[90:93], v57 offset:6656
	ds_read_b128 v[94:97], v57 offset:6672
	ds_read_b128 v[98:101], v57 offset:6688
	ds_read_b128 v[102:105], v57 offset:6704
	s_waitcnt vmcnt(24) lgkmcnt(4)
	v_pk_fma_f32 v[38:39], v[128:129], v[106:107], v[38:39] op_sel:[1,0,0]
	v_pk_fma_f32 v[40:41], v[128:129], v[108:109], v[40:41] op_sel:[1,0,0]
	v_pk_fma_f32 v[42:43], v[128:129], v[110:111], v[42:43] op_sel:[1,0,0]
	v_pk_fma_f32 v[44:45], v[128:129], v[112:113], v[44:45] op_sel:[1,0,0]
	v_pk_fma_f32 v[46:47], v[128:129], v[114:115], v[46:47] op_sel:[1,0,0]
	v_pk_fma_f32 v[48:49], v[128:129], v[116:117], v[48:49] op_sel:[1,0,0]
	v_pk_fma_f32 v[50:51], v[128:129], v[118:119], v[50:51] op_sel:[1,0,0]
	v_pk_fma_f32 v[36:37], v[128:129], v[120:121], v[36:37] op_sel:[1,0,0]
	ds_read_b128 v[106:109], v57 offset:6720
	ds_read_b128 v[110:113], v57 offset:6736
	ds_read_b128 v[114:117], v57 offset:6752
	ds_read_b128 v[118:121], v57 offset:6768
	s_waitcnt vmcnt(23) lgkmcnt(4)
; #define LAS __attribute__((address_space(3)))
; __device__ __forceinline__ void phase_prep(const Args& a, LAS unsigned char* lds) {
;     ...
;             for (int k = kbeg; k < kbeg + 128; ++k) { const float wv = w[(size_t)k * 6144];
;                 const LAS f32x4* s4 = (const LAS f32x4*)(sc + k * 16);
; #pragma unroll
;                 for (int q = 0; q < 4; ++q) { const f32x4 s = s4[q]; acc[4 * q] += s[0] * wv; acc[4 * q + 1] += s[1] * wv; acc[4 * q + 2] += s[2] * wv; acc[4 * q + 3] += s[3] * wv; } }
	v_pk_fma_f32 v[38:39], v[130:131], v[90:91], v[38:39] op_sel_hi:[0,1,1]
	v_pk_fma_f32 v[40:41], v[130:131], v[92:93], v[40:41] op_sel_hi:[0,1,1]
	v_pk_fma_f32 v[42:43], v[130:131], v[94:95], v[42:43] op_sel_hi:[0,1,1]
	v_pk_fma_f32 v[44:45], v[130:131], v[96:97], v[44:45] op_sel_hi:[0,1,1]
	v_pk_fma_f32 v[46:47], v[130:131], v[98:99], v[46:47] op_sel_hi:[0,1,1]
	v_pk_fma_f32 v[48:49], v[130:131], v[100:101], v[48:49] op_sel_hi:[0,1,1]
	v_pk_fma_f32 v[50:51], v[130:131], v[102:103], v[50:51] op_sel_hi:[0,1,1]
	v_pk_fma_f32 v[36:37], v[130:131], v[104:105], v[36:37] op_sel_hi:[0,1,1]
	ds_read_b128 v[90:93], v57 offset:6784
	ds_read_b128 v[94:97], v57 offset:6800
	ds_read_b128 v[98:101], v57 offset:6816
	ds_read_b128 v[102:105], v57 offset:6832
	s_waitcnt vmcnt(22) lgkmcnt(4)
	v_pk_fma_f32 v[38:39], v[130:131], v[106:107], v[38:39] op_sel:[1,0,0]
	v_pk_fma_f32 v[40:41], v[130:131], v[108:109], v[40:41] op_sel:[1,0,0]
	v_pk_fma_f32 v[42:43], v[130:131], v[110:111], v[42:43] op_sel:[1,0,0]
	v_pk_fma_f32 v[44:45], v[130:131], v[112:113], v[44:45] op_sel:[1,0,0]
	v_pk_fma_f32 v[46:47], v[130:131], v[114:115], v[46:47] op_sel:[1,0,0]
	v_pk_fma_f32 v[48:49], v[130:131], v[116:117], v[48:49] op_sel:[1,0,0]
	v_pk_fma_f32 v[50:51], v[130:131], v[118:119], v[50:51] op_sel:[1,0,0]
	v_pk_fma_f32 v[36:37], v[130:131], v[120:121], v[36:37] op_sel:[1,0,0]
	ds_read_b128 v[106:109], v57 offset:6848
	ds_read_b128 v[110:113], v57 offset:6864
	ds_read_b128 v[114:117], v57 offset:6880
	ds_read_b128 v[118:121], v57 offset:6896
	s_waitcnt vmcnt(21) lgkmcnt(4)
	v_pk_fma_f32 v[38:39], v[132:133], v[90:91], v[38:39] op_sel_hi:[0,1,1]
	v_pk_fma_f32 v[40:41], v[132:133], v[92:93], v[40:41] op_sel_hi:[0,1,1]
	v_pk_fma_f32 v[42:43], v[132:133], v[94:95], v[42:43] op_sel_hi:[0,1,1]
	v_pk_fma_f32 v[44:45], v[132:133], v[96:97], v[44:45] op_sel_hi:[0,1,1]
	v_pk_fma_f32 v[46:47], v[132:133], v[98:99], v[46:47] op_sel_hi:[0,1,1]
	v_pk_fma_f32 v[48:49], v[132:133], v[100:101], v[48:49] op_sel_hi:[0,1,1]
	v_pk_fma_f32 v[50:51], v[132:133], v[102:103], v[50:51] op_sel_hi:[0,1,1]
	v_pk_fma_f32 v[36:37], v[132:133], v[104:105], v[36:37] op_sel_hi:[0,1,1]
	ds_read_b128 v[90:93], v57 offset:6912
	ds_read_b128 v[94:97], v57 offset:6928
	ds_read_b128 v[98:101], v57 offset:6944
	ds_read_b128 v[102:105], v57 offset:6960
	s_waitcnt vmcnt(20) lgkmcnt(4)
	v_pk_fma_f32 v[38:39], v[132:133], v[106:107], v[38:39] op_sel:[1,0,0]
	v_pk_fma_f32 v[40:41], v[132:133], v[108:109], v[40:41] op_sel:[1,0,0]
	v_pk_fma_f32 v[42:43], v[132:133], v[110:111], v[42:43] op_sel:[1,0,0]
	v_pk_fma_f32 v[44:45], v[132:133], v[112:113], v[44:45] op_sel:[1,0,0]
	v_pk_fma_f32 v[46:47], v[132:133], v[114:115], v[46:47] op_sel:[1,0,0]
	v_pk_fma_f32 v[48:49], v[132:133], v[116:117], v[48:49] op_sel:[1,0,0]
	v_pk_fma_f32 v[50:51], v[132:133], v[118:119], v[50:51] op_sel:[1,0,0]
	v_pk_fma_f32 v[36:37], v[132:133], v[120:121], v[36:37] op_sel:[1,0,0]
	ds_read_b128 v[106:109], v57 offset:6976
	ds_read_b128 v[110:113], v57 offset:6992
	ds_read_b128 v[114:117], v57 offset:7008
	ds_read_b128 v[118:121], v57 offset:7024
	s_waitcnt vmcnt(19) lgkmcnt(4)
	v_pk_fma_f32 v[38:39], v[134:135], v[90:91], v[38:39] op_sel_hi:[0,1,1]
	v_pk_fma_f32 v[40:41], v[134:135], v[92:93], v[40:41] op_sel_hi:[0,1,1]
	v_pk_fma_f32 v[42:43], v[134:135], v[94:95], v[42:43] op_sel_hi:[0,1,1]
	v_pk_fma_f32 v[44:45], v[134:135], v[96:97], v[44:45] op_sel_hi:[0,1,1]
	v_pk_fma_f32 v[46:47], v[134:135], v[98:99], v[46:47] op_sel_hi:[0,1,1]
	v_pk_fma_f32 v[48:49], v[134:135], v[100:101], v[48:49] op_sel_hi:[0,1,1]
	v_pk_fma_f32 v[50:51], v[134:135], v[102:103], v[50:51] op_sel_hi:[0,1,1]
	v_pk_fma_f32 v[36:37], v[134:135], v[104:105], v[36:37] op_sel_hi:[0,1,1]
	ds_read_b128 v[90:93], v57 offset:7040
	ds_read_b128 v[94:97], v57 offset:7056
	ds_read_b128 v[98:101], v57 offset:7072
	ds_read_b128 v[102:105], v57 offset:7088
	s_waitcnt vmcnt(18) lgkmcnt(4)
	v_pk_fma_f32 v[38:39], v[134:135], v[106:107], v[38:39] op_sel:[1,0,0]
	v_pk_fma_f32 v[40:41], v[134:135], v[108:109], v[40:41] op_sel:[1,0,0]
	v_pk_fma_f32 v[42:43], v[134:135], v[110:111], v[42:43] op_sel:[1,0,0]
	v_pk_fma_f32 v[44:45], v[134:135], v[112:113], v[44:45] op_sel:[1,0,0]
	v_pk_fma_f32 v[46:47], v[134:135], v[114:115], v[46:47] op_sel:[1,0,0]
	v_pk_fma_f32 v[48:49], v[134:135], v[116:117], v[48:49] op_sel:[1,0,0]
	v_pk_fma_f32 v[50:51], v[134:135], v[118:119], v[50:51] op_sel:[1,0,0]
	v_pk_fma_f32 v[36:37], v[134:135], v[120:121], v[36:37] op_sel:[1,0,0]
	ds_read_b128 v[106:109], v57 offset:7104
	ds_read_b128 v[110:113], v57 offset:7120
	ds_read_b128 v[114:117], v57 offset:7136
	ds_read_b128 v[118:121], v57 offset:7152
	s_waitcnt vmcnt(17) lgkmcnt(4)
	v_pk_fma_f32 v[38:39], v[136:137], v[90:91], v[38:39] op_sel_hi:[0,1,1]
	v_pk_fma_f32 v[40:41], v[136:137], v[92:93], v[40:41] op_sel_hi:[0,1,1]
	v_pk_fma_f32 v[42:43], v[136:137], v[94:95], v[42:43] op_sel_hi:[0,1,1]
	v_pk_fma_f32 v[44:45], v[136:137], v[96:97], v[44:45] op_sel_hi:[0,1,1]
	v_pk_fma_f32 v[46:47], v[136:137], v[98:99], v[46:47] op_sel_hi:[0,1,1]
	v_pk_fma_f32 v[48:49], v[136:137], v[100:101], v[48:49] op_sel_hi:[0,1,1]
	v_pk_fma_f32 v[50:51], v[136:137], v[102:103], v[50:51] op_sel_hi:[0,1,1]
	v_pk_fma_f32 v[36:37], v[136:137], v[104:105], v[36:37] op_sel_hi:[0,1,1]
	ds_read_b128 v[90:93], v57 offset:7168
	ds_read_b128 v[94:97], v57 offset:7184
	ds_read_b128 v[98:101], v57 offset:7200
	ds_read_b128 v[102:105], v57 offset:7216
	s_waitcnt vmcnt(16) lgkmcnt(4)
; #define LAS __attribute__((address_space(3)))
; __device__ __forceinline__ void phase_prep(const Args& a, LAS unsigned char* lds) {
;     ...
;             for (int k = kbeg; k < kbeg + 128; ++k) { const float wv = w[(size_t)k * 6144];
;                 const LAS f32x4* s4 = (const LAS f32x4*)(sc + k * 16);
; #pragma unroll
;                 for (int q = 0; q < 4; ++q) { const f32x4 s = s4[q]; acc[4 * q] += s[0] * wv; acc[4 * q + 1] += s[1] * wv; acc[4 * q + 2] += s[2] * wv; acc[4 * q + 3] += s[3] * wv; } }
	v_pk_fma_f32 v[38:39], v[136:137], v[106:107], v[38:39] op_sel:[1,0,0]
	v_pk_fma_f32 v[40:41], v[136:137], v[108:109], v[40:41] op_sel:[1,0,0]
	v_pk_fma_f32 v[42:43], v[136:137], v[110:111], v[42:43] op_sel:[1,0,0]
	v_pk_fma_f32 v[44:45], v[136:137], v[112:113], v[44:45] op_sel:[1,0,0]
	v_pk_fma_f32 v[46:47], v[136:137], v[114:115], v[46:47] op_sel:[1,0,0]
	v_pk_fma_f32 v[48:49], v[136:137], v[116:117], v[48:49] op_sel:[1,0,0]
	v_pk_fma_f32 v[50:51], v[136:137], v[118:119], v[50:51] op_sel:[1,0,0]
	v_pk_fma_f32 v[36:37], v[136:137], v[120:121], v[36:37] op_sel:[1,0,0]
	ds_read_b128 v[106:109], v57 offset:7232
	ds_read_b128 v[110:113], v57 offset:7248
	ds_read_b128 v[114:117], v57 offset:7264
	ds_read_b128 v[118:121], v57 offset:7280
	s_waitcnt vmcnt(15) lgkmcnt(4)
	v_pk_fma_f32 v[38:39], v[138:139], v[90:91], v[38:39] op_sel_hi:[0,1,1]
	v_pk_fma_f32 v[40:41], v[138:139], v[92:93], v[40:41] op_sel_hi:[0,1,1]
	v_pk_fma_f32 v[42:43], v[138:139], v[94:95], v[42:43] op_sel_hi:[0,1,1]
	v_pk_fma_f32 v[44:45], v[138:139], v[96:97], v[44:45] op_sel_hi:[0,1,1]
	v_pk_fma_f32 v[46:47], v[138:139], v[98:99], v[46:47] op_sel_hi:[0,1,1]
	v_pk_fma_f32 v[48:49], v[138:139], v[100:101], v[48:49] op_sel_hi:[0,1,1]
	v_pk_fma_f32 v[50:51], v[138:139], v[102:103], v[50:51] op_sel_hi:[0,1,1]
	v_pk_fma_f32 v[36:37], v[138:139], v[104:105], v[36:37] op_sel_hi:[0,1,1]
	ds_read_b128 v[90:93], v57 offset:7296
	ds_read_b128 v[94:97], v57 offset:7312
	ds_read_b128 v[98:101], v57 offset:7328
	ds_read_b128 v[102:105], v57 offset:7344
	s_waitcnt vmcnt(14) lgkmcnt(4)
	v_pk_fma_f32 v[38:39], v[138:139], v[106:107], v[38:39] op_sel:[1,0,0]
	v_pk_fma_f32 v[40:41], v[138:139], v[108:109], v[40:41] op_sel:[1,0,0]
	v_pk_fma_f32 v[42:43], v[138:139], v[110:111], v[42:43] op_sel:[1,0,0]
	v_pk_fma_f32 v[44:45], v[138:139], v[112:113], v[44:45] op_sel:[1,0,0]
	v_pk_fma_f32 v[46:47], v[138:139], v[114:115], v[46:47] op_sel:[1,0,0]
	v_pk_fma_f32 v[48:49], v[138:139], v[116:117], v[48:49] op_sel:[1,0,0]
	v_pk_fma_f32 v[50:51], v[138:139], v[118:119], v[50:51] op_sel:[1,0,0]
	v_pk_fma_f32 v[36:37], v[138:139], v[120:121], v[36:37] op_sel:[1,0,0]
	ds_read_b128 v[106:109], v57 offset:7360
	ds_read_b128 v[110:113], v57 offset:7376
	ds_read_b128 v[114:117], v57 offset:7392
	ds_read_b128 v[118:121], v57 offset:7408
	s_waitcnt vmcnt(13) lgkmcnt(4)
	v_pk_fma_f32 v[38:39], v[140:141], v[90:91], v[38:39] op_sel_hi:[0,1,1]
	v_pk_fma_f32 v[40:41], v[140:141], v[92:93], v[40:41] op_sel_hi:[0,1,1]
	v_pk_fma_f32 v[42:43], v[140:141], v[94:95], v[42:43] op_sel_hi:[0,1,1]
	v_pk_fma_f32 v[44:45], v[140:141], v[96:97], v[44:45] op_sel_hi:[0,1,1]
	v_pk_fma_f32 v[46:47], v[140:141], v[98:99], v[46:47] op_sel_hi:[0,1,1]
	v_pk_fma_f32 v[48:49], v[140:141], v[100:101], v[48:49] op_sel_hi:[0,1,1]
	v_pk_fma_f32 v[50:51], v[140:141], v[102:103], v[50:51] op_sel_hi:[0,1,1]
	v_pk_fma_f32 v[36:37], v[140:141], v[104:105], v[36:37] op_sel_hi:[0,1,1]
	ds_read_b128 v[90:93], v57 offset:7424
	ds_read_b128 v[94:97], v57 offset:7440
	ds_read_b128 v[98:101], v57 offset:7456
	ds_read_b128 v[102:105], v57 offset:7472
	s_waitcnt vmcnt(12) lgkmcnt(4)
	v_pk_fma_f32 v[38:39], v[140:141], v[106:107], v[38:39] op_sel:[1,0,0]
	v_pk_fma_f32 v[40:41], v[140:141], v[108:109], v[40:41] op_sel:[1,0,0]
	v_pk_fma_f32 v[42:43], v[140:141], v[110:111], v[42:43] op_sel:[1,0,0]
	v_pk_fma_f32 v[44:45], v[140:141], v[112:113], v[44:45] op_sel:[1,0,0]
	v_pk_fma_f32 v[46:47], v[140:141], v[114:115], v[46:47] op_sel:[1,0,0]
	v_pk_fma_f32 v[48:49], v[140:141], v[116:117], v[48:49] op_sel:[1,0,0]
	v_pk_fma_f32 v[50:51], v[140:141], v[118:119], v[50:51] op_sel:[1,0,0]
	v_pk_fma_f32 v[36:37], v[140:141], v[120:121], v[36:37] op_sel:[1,0,0]
	ds_read_b128 v[106:109], v57 offset:7488
	ds_read_b128 v[110:113], v57 offset:7504
	ds_read_b128 v[114:117], v57 offset:7520
	ds_read_b128 v[118:121], v57 offset:7536
	s_waitcnt vmcnt(11) lgkmcnt(4)
	v_pk_fma_f32 v[38:39], v[142:143], v[90:91], v[38:39] op_sel_hi:[0,1,1]
	v_pk_fma_f32 v[40:41], v[142:143], v[92:93], v[40:41] op_sel_hi:[0,1,1]
	v_pk_fma_f32 v[42:43], v[142:143], v[94:95], v[42:43] op_sel_hi:[0,1,1]
	v_pk_fma_f32 v[44:45], v[142:143], v[96:97], v[44:45] op_sel_hi:[0,1,1]
	v_pk_fma_f32 v[46:47], v[142:143], v[98:99], v[46:47] op_sel_hi:[0,1,1]
	v_pk_fma_f32 v[48:49], v[142:143], v[100:101], v[48:49] op_sel_hi:[0,1,1]
	v_pk_fma_f32 v[50:51], v[142:143], v[102:103], v[50:51] op_sel_hi:[0,1,1]
	v_pk_fma_f32 v[36:37], v[142:143], v[104:105], v[36:37] op_sel_hi:[0,1,1]
	ds_read_b128 v[90:93], v57 offset:7552
	ds_read_b128 v[94:97], v57 offset:7568
	ds_read_b128 v[98:101], v57 offset:7584
	ds_read_b128 v[102:105], v57 offset:7600
	s_waitcnt vmcnt(10) lgkmcnt(4)
	v_pk_fma_f32 v[38:39], v[142:143], v[106:107], v[38:39] op_sel:[1,0,0]
	v_pk_fma_f32 v[40:41], v[142:143], v[108:109], v[40:41] op_sel:[1,0,0]
	v_pk_fma_f32 v[42:43], v[142:143], v[110:111], v[42:43] op_sel:[1,0,0]
	v_pk_fma_f32 v[44:45], v[142:143], v[112:113], v[44:45] op_sel:[1,0,0]
	v_pk_fma_f32 v[46:47], v[142:143], v[114:115], v[46:47] op_sel:[1,0,0]
	v_pk_fma_f32 v[48:49], v[142:143], v[116:117], v[48:49] op_sel:[1,0,0]
	v_pk_fma_f32 v[50:51], v[142:143], v[118:119], v[50:51] op_sel:[1,0,0]
	v_pk_fma_f32 v[36:37], v[142:143], v[120:121], v[36:37] op_sel:[1,0,0]
	ds_read_b128 v[106:109], v57 offset:7616
	ds_read_b128 v[110:113], v57 offset:7632
	ds_read_b128 v[114:117], v57 offset:7648
	ds_read_b128 v[118:121], v57 offset:7664
	s_waitcnt vmcnt(9) lgkmcnt(4)
; #define LAS __attribute__((address_space(3)))
; __device__ __forceinline__ void phase_prep(const Args& a, LAS unsigned char* lds) {
;     ...
;             for (int k = kbeg; k < kbeg + 128; ++k) { const float wv = w[(size_t)k * 6144];
;                 const LAS f32x4* s4 = (const LAS f32x4*)(sc + k * 16);
; #pragma unroll
;                 for (int q = 0; q < 4; ++q) { const f32x4 s = s4[q]; acc[4 * q] += s[0] * wv; acc[4 * q + 1] += s[1] * wv; acc[4 * q + 2] += s[2] * wv; acc[4 * q + 3] += s[3] * wv; } }
	v_pk_fma_f32 v[38:39], v[144:145], v[90:91], v[38:39] op_sel_hi:[0,1,1]
	v_pk_fma_f32 v[40:41], v[144:145], v[92:93], v[40:41] op_sel_hi:[0,1,1]
	v_pk_fma_f32 v[42:43], v[144:145], v[94:95], v[42:43] op_sel_hi:[0,1,1]
	v_pk_fma_f32 v[44:45], v[144:145], v[96:97], v[44:45] op_sel_hi:[0,1,1]
	v_pk_fma_f32 v[46:47], v[144:145], v[98:99], v[46:47] op_sel_hi:[0,1,1]
	v_pk_fma_f32 v[48:49], v[144:145], v[100:101], v[48:49] op_sel_hi:[0,1,1]
	v_pk_fma_f32 v[50:51], v[144:145], v[102:103], v[50:51] op_sel_hi:[0,1,1]
	v_pk_fma_f32 v[36:37], v[144:145], v[104:105], v[36:37] op_sel_hi:[0,1,1]
	ds_read_b128 v[90:93], v57 offset:7680
	ds_read_b128 v[94:97], v57 offset:7696
	ds_read_b128 v[98:101], v57 offset:7712
	ds_read_b128 v[102:105], v57 offset:7728
	s_waitcnt vmcnt(8) lgkmcnt(4)
	v_pk_fma_f32 v[38:39], v[144:145], v[106:107], v[38:39] op_sel:[1,0,0]
	v_pk_fma_f32 v[40:41], v[144:145], v[108:109], v[40:41] op_sel:[1,0,0]
	v_pk_fma_f32 v[42:43], v[144:145], v[110:111], v[42:43] op_sel:[1,0,0]
	v_pk_fma_f32 v[44:45], v[144:145], v[112:113], v[44:45] op_sel:[1,0,0]
	v_pk_fma_f32 v[46:47], v[144:145], v[114:115], v[46:47] op_sel:[1,0,0]
	v_pk_fma_f32 v[48:49], v[144:145], v[116:117], v[48:49] op_sel:[1,0,0]
	v_pk_fma_f32 v[50:51], v[144:145], v[118:119], v[50:51] op_sel:[1,0,0]
	v_pk_fma_f32 v[36:37], v[144:145], v[120:121], v[36:37] op_sel:[1,0,0]
	ds_read_b128 v[106:109], v57 offset:7744
	ds_read_b128 v[110:113], v57 offset:7760
	ds_read_b128 v[114:117], v57 offset:7776
	ds_read_b128 v[118:121], v57 offset:7792
	s_waitcnt vmcnt(7) lgkmcnt(4)
	v_pk_fma_f32 v[38:39], v[146:147], v[90:91], v[38:39] op_sel_hi:[0,1,1]
	v_pk_fma_f32 v[40:41], v[146:147], v[92:93], v[40:41] op_sel_hi:[0,1,1]
	v_pk_fma_f32 v[42:43], v[146:147], v[94:95], v[42:43] op_sel_hi:[0,1,1]
	v_pk_fma_f32 v[44:45], v[146:147], v[96:97], v[44:45] op_sel_hi:[0,1,1]
	v_pk_fma_f32 v[46:47], v[146:147], v[98:99], v[46:47] op_sel_hi:[0,1,1]
	v_pk_fma_f32 v[48:49], v[146:147], v[100:101], v[48:49] op_sel_hi:[0,1,1]
	v_pk_fma_f32 v[50:51], v[146:147], v[102:103], v[50:51] op_sel_hi:[0,1,1]
	v_pk_fma_f32 v[36:37], v[146:147], v[104:105], v[36:37] op_sel_hi:[0,1,1]
	ds_read_b128 v[90:93], v57 offset:7808
	ds_read_b128 v[94:97], v57 offset:7824
	ds_read_b128 v[98:101], v57 offset:7840
	ds_read_b128 v[102:105], v57 offset:7856
	s_waitcnt vmcnt(6) lgkmcnt(4)
	v_pk_fma_f32 v[38:39], v[146:147], v[106:107], v[38:39] op_sel:[1,0,0]
	v_pk_fma_f32 v[40:41], v[146:147], v[108:109], v[40:41] op_sel:[1,0,0]
	v_pk_fma_f32 v[42:43], v[146:147], v[110:111], v[42:43] op_sel:[1,0,0]
	v_pk_fma_f32 v[44:45], v[146:147], v[112:113], v[44:45] op_sel:[1,0,0]
	v_pk_fma_f32 v[46:47], v[146:147], v[114:115], v[46:47] op_sel:[1,0,0]
	v_pk_fma_f32 v[48:49], v[146:147], v[116:117], v[48:49] op_sel:[1,0,0]
	v_pk_fma_f32 v[50:51], v[146:147], v[118:119], v[50:51] op_sel:[1,0,0]
	v_pk_fma_f32 v[36:37], v[146:147], v[120:121], v[36:37] op_sel:[1,0,0]
	ds_read_b128 v[106:109], v57 offset:7872
	ds_read_b128 v[110:113], v57 offset:7888
	ds_read_b128 v[114:117], v57 offset:7904
	ds_read_b128 v[118:121], v57 offset:7920
	s_waitcnt vmcnt(5) lgkmcnt(4)
	v_pk_fma_f32 v[38:39], v[148:149], v[90:91], v[38:39] op_sel_hi:[0,1,1]
	v_pk_fma_f32 v[40:41], v[148:149], v[92:93], v[40:41] op_sel_hi:[0,1,1]
	v_pk_fma_f32 v[42:43], v[148:149], v[94:95], v[42:43] op_sel_hi:[0,1,1]
	v_pk_fma_f32 v[44:45], v[148:149], v[96:97], v[44:45] op_sel_hi:[0,1,1]
	v_pk_fma_f32 v[46:47], v[148:149], v[98:99], v[46:47] op_sel_hi:[0,1,1]
	v_pk_fma_f32 v[48:49], v[148:149], v[100:101], v[48:49] op_sel_hi:[0,1,1]
	v_pk_fma_f32 v[50:51], v[148:149], v[102:103], v[50:51] op_sel_hi:[0,1,1]
	v_pk_fma_f32 v[36:37], v[148:149], v[104:105], v[36:37] op_sel_hi:[0,1,1]
	ds_read_b128 v[90:93], v57 offset:7936
	ds_read_b128 v[94:97], v57 offset:7952
	ds_read_b128 v[98:101], v57 offset:7968
	ds_read_b128 v[102:105], v57 offset:7984
	s_waitcnt vmcnt(4) lgkmcnt(4)
; #define LAS __attribute__((address_space(3)))
; __device__ __forceinline__ void phase_prep(const Args& a, LAS unsigned char* lds) {
;     ...
;             for (int k = kbeg; k < kbeg + 128; ++k) { const float wv = w[(size_t)k * 6144];
;                 const LAS f32x4* s4 = (const LAS f32x4*)(sc + k * 16);
; #pragma unroll
;                 for (int q = 0; q < 4; ++q) { const f32x4 s = s4[q]; acc[4 * q] += s[0] * wv; acc[4 * q + 1] += s[1] * wv; acc[4 * q + 2] += s[2] * wv; acc[4 * q + 3] += s[3] * wv; } }
; #pragma unroll
;             for (int b = 0; b < 16; ++b) red[(wave * 16 + b) * 64 + lane] = acc[b];
;             __syncthreads();
;             float* mod = (float*)(ws + WS_MOD);
;             for (int e = tid; e < 1024; e += NTHREADS) { const int b = e >> 6, n = e & 63; float s = 0.f;
; #pragma unroll
;                 for (int wv = 0; wv < 8; ++wv) s += red[(wv * 16 + b) * 64 + n];
;                 mod[((size_t)l * 16 + b) * 6144 + n0 + n] = s + a.in[3][l * 6144 + n0 + n]; }
	v_pk_fma_f32 v[38:39], v[148:149], v[106:107], v[38:39] op_sel:[1,0,0]
	v_pk_fma_f32 v[40:41], v[148:149], v[108:109], v[40:41] op_sel:[1,0,0]
	v_pk_fma_f32 v[42:43], v[148:149], v[110:111], v[42:43] op_sel:[1,0,0]
	v_pk_fma_f32 v[44:45], v[148:149], v[112:113], v[44:45] op_sel:[1,0,0]
	v_pk_fma_f32 v[46:47], v[148:149], v[114:115], v[46:47] op_sel:[1,0,0]
	v_pk_fma_f32 v[48:49], v[148:149], v[116:117], v[48:49] op_sel:[1,0,0]
	v_pk_fma_f32 v[50:51], v[148:149], v[118:119], v[50:51] op_sel:[1,0,0]
	v_pk_fma_f32 v[36:37], v[148:149], v[120:121], v[36:37] op_sel:[1,0,0]
	ds_read_b128 v[106:109], v57 offset:8000
	ds_read_b128 v[110:113], v57 offset:8016
	ds_read_b128 v[114:117], v57 offset:8032
	ds_read_b128 v[118:121], v57 offset:8048
	s_waitcnt vmcnt(3) lgkmcnt(4)
	v_pk_fma_f32 v[38:39], v[150:151], v[90:91], v[38:39] op_sel_hi:[0,1,1]
	v_pk_fma_f32 v[40:41], v[150:151], v[92:93], v[40:41] op_sel_hi:[0,1,1]
	v_pk_fma_f32 v[42:43], v[150:151], v[94:95], v[42:43] op_sel_hi:[0,1,1]
	v_pk_fma_f32 v[44:45], v[150:151], v[96:97], v[44:45] op_sel_hi:[0,1,1]
	v_pk_fma_f32 v[46:47], v[150:151], v[98:99], v[46:47] op_sel_hi:[0,1,1]
	v_pk_fma_f32 v[48:49], v[150:151], v[100:101], v[48:49] op_sel_hi:[0,1,1]
	v_pk_fma_f32 v[50:51], v[150:151], v[102:103], v[50:51] op_sel_hi:[0,1,1]
	v_pk_fma_f32 v[36:37], v[150:151], v[104:105], v[36:37] op_sel_hi:[0,1,1]
	ds_read_b128 v[90:93], v57 offset:8064
	ds_read_b128 v[94:97], v57 offset:8080
	ds_read_b128 v[98:101], v57 offset:8096
	ds_read_b128 v[102:105], v57 offset:8112
	s_waitcnt vmcnt(2) lgkmcnt(4)
	v_pk_fma_f32 v[38:39], v[150:151], v[106:107], v[38:39] op_sel:[1,0,0]
	v_pk_fma_f32 v[40:41], v[150:151], v[108:109], v[40:41] op_sel:[1,0,0]
	v_pk_fma_f32 v[42:43], v[150:151], v[110:111], v[42:43] op_sel:[1,0,0]
	v_pk_fma_f32 v[44:45], v[150:151], v[112:113], v[44:45] op_sel:[1,0,0]
	v_pk_fma_f32 v[46:47], v[150:151], v[114:115], v[46:47] op_sel:[1,0,0]
	v_pk_fma_f32 v[48:49], v[150:151], v[116:117], v[48:49] op_sel:[1,0,0]
	v_pk_fma_f32 v[50:51], v[150:151], v[118:119], v[50:51] op_sel:[1,0,0]
	v_pk_fma_f32 v[36:37], v[150:151], v[120:121], v[36:37] op_sel:[1,0,0]
	ds_read_b128 v[106:109], v57 offset:8128
	ds_read_b128 v[110:113], v57 offset:8144
	ds_read_b128 v[114:117], v57 offset:8160
	ds_read_b128 v[118:121], v57 offset:8176
	s_waitcnt vmcnt(1) lgkmcnt(4)
	v_pk_fma_f32 v[38:39], v[152:153], v[90:91], v[38:39] op_sel_hi:[0,1,1]
	v_pk_fma_f32 v[40:41], v[152:153], v[92:93], v[40:41] op_sel_hi:[0,1,1]
	v_pk_fma_f32 v[42:43], v[152:153], v[94:95], v[42:43] op_sel_hi:[0,1,1]
	v_pk_fma_f32 v[44:45], v[152:153], v[96:97], v[44:45] op_sel_hi:[0,1,1]
	v_pk_fma_f32 v[46:47], v[152:153], v[98:99], v[46:47] op_sel_hi:[0,1,1]
	v_pk_fma_f32 v[48:49], v[152:153], v[100:101], v[48:49] op_sel_hi:[0,1,1]
	v_pk_fma_f32 v[50:51], v[152:153], v[102:103], v[50:51] op_sel_hi:[0,1,1]
	v_pk_fma_f32 v[36:37], v[152:153], v[104:105], v[36:37] op_sel_hi:[0,1,1]
	s_waitcnt vmcnt(0) lgkmcnt(0)
	v_pk_fma_f32 v[38:39], v[152:153], v[106:107], v[38:39] op_sel:[1,0,0]
	v_pk_fma_f32 v[40:41], v[152:153], v[108:109], v[40:41] op_sel:[1,0,0]
	v_pk_fma_f32 v[42:43], v[152:153], v[110:111], v[42:43] op_sel:[1,0,0]
	v_pk_fma_f32 v[44:45], v[152:153], v[112:113], v[44:45] op_sel:[1,0,0]
	v_pk_fma_f32 v[46:47], v[152:153], v[114:115], v[46:47] op_sel:[1,0,0]
	v_pk_fma_f32 v[48:49], v[152:153], v[116:117], v[48:49] op_sel:[1,0,0]
	v_pk_fma_f32 v[50:51], v[152:153], v[118:119], v[50:51] op_sel:[1,0,0]
	v_pk_fma_f32 v[36:37], v[152:153], v[120:121], v[36:37] op_sel:[1,0,0]
	ds_write2st64_b32 v56, v38, v39 offset1:1
	ds_write2st64_b32 v56, v40, v41 offset0:2 offset1:3
	ds_write2st64_b32 v56, v42, v43 offset0:4 offset1:5
	ds_write2st64_b32 v56, v44, v45 offset0:6 offset1:7
	ds_write2st64_b32 v56, v46, v47 offset0:8 offset1:9
	ds_write2st64_b32 v56, v48, v49 offset0:10 offset1:11
	ds_write2st64_b32 v56, v50, v51 offset0:12 offset1:13
	ds_write2st64_b32 v56, v36, v37 offset0:14 offset1:15
	s_waitcnt lgkmcnt(0)
	s_barrier
	s_and_saveexec_b64 s[14:15], s[4:5]
	s_cbranch_execz .LBB0_10
	s_mul_i32 s34, s12, 0x1800
	s_add_i32 s34, s34, s10
	v_or_b32_e32 v2, s34, v1
	v_ashrrev_i32_e32 v3, 31, v2
	s_lshl_b64 s[12:13], s[12:13], 4
	v_lshl_add_u64 v[2:3], v[2:3], 2, s[74:75]
	v_lshl_add_u64 v[4:5], s[10:11], 2, v[28:29]
	s_mov_b64 s[10:11], 0
	v_mov_b32_e32 v6, v26
